# hoisted serialized epilogue loads: EpiProj gate/merge loads (2 batches), EpiQ/EpiKV rstd partial-sum loads; all loads issued up front with one wait
# speedup vs baseline: 1.0135x; 1.0135x over previous
; __device__ __forceinline__ float rstd4(const float* pp, int row, float invn) { const f32x4 a = *(const f32x4*)(pp + (size_t)row * 4); return rsqrtf(((a.x + a.y) + (a.z + a.w)) * invn + 1e-6f); }
.LBB0_1065:
	v_lshl_or_b32 v158, s51, 8, v142
	v_lshl_add_u32 v138, s50, 8, v140
	v_ashrrev_i32_e32 v159, 31, v158
	v_readlane_b32 s28, v254, 10
	v_ashrrev_i32_e32 v139, 31, v138
	v_readlane_b32 s29, v254, 11
	s_mov_b32 s50, 0x800000
	s_nop 0
	v_lshl_add_u64 v[154:155], v[138:139], 4, s[28:29]
	v_mov_b32_e32 v214, v138
	v_ashrrev_i32_e32 v215, 31, v214
	v_lshl_add_u64 v[214:215], v[214:215], 4, s[28:29]
	global_load_dwordx4 v[162:165], v[214:215], off
	v_add_u32_e32 v214, 16, v138
	v_ashrrev_i32_e32 v215, 31, v214
	v_lshl_add_u64 v[214:215], v[214:215], 4, s[28:29]
	global_load_dwordx4 v[186:189], v[214:215], off
	v_add_u32_e32 v214, 32, v138
	v_ashrrev_i32_e32 v215, 31, v214
	v_lshl_add_u64 v[214:215], v[214:215], 4, s[28:29]
	global_load_dwordx4 v[190:193], v[214:215], off
	v_add_u32_e32 v214, 48, v138
	v_ashrrev_i32_e32 v215, 31, v214
	v_lshl_add_u64 v[214:215], v[214:215], 4, s[28:29]
	global_load_dwordx4 v[194:197], v[214:215], off
	v_add_u32_e32 v214, 128, v138
	v_ashrrev_i32_e32 v215, 31, v214
	v_lshl_add_u64 v[214:215], v[214:215], 4, s[28:29]
	global_load_dwordx4 v[198:201], v[214:215], off
	v_add_u32_e32 v214, 144, v138
	v_ashrrev_i32_e32 v215, 31, v214
	v_lshl_add_u64 v[214:215], v[214:215], 4, s[28:29]
	global_load_dwordx4 v[202:205], v[214:215], off
	v_add_u32_e32 v214, 160, v138
	v_ashrrev_i32_e32 v215, 31, v214
	v_lshl_add_u64 v[214:215], v[214:215], 4, s[28:29]
	global_load_dwordx4 v[206:209], v[214:215], off
	v_add_u32_e32 v214, 176, v138
	v_ashrrev_i32_e32 v215, 31, v214
	v_lshl_add_u64 v[214:215], v[214:215], 4, s[28:29]
	global_load_dwordx4 v[210:213], v[214:215], off
	s_waitcnt vmcnt(0)
	v_mov_b32_e32 v154, v162
	v_mov_b32_e32 v155, v163
	v_mov_b32_e32 v156, v164
	v_mov_b32_e32 v157, v165
	v_mov_b32_e32 v160, v155
	v_mov_b32_e32 v161, v156
	v_mov_b32_e32 v155, v157
	v_pk_add_f32 v[154:155], v[160:161], v[154:155]
	s_nop 0
	v_add_f32_e32 v139, v154, v155
	v_fmamk_f32 v139, v139, 0x3b800000, v171
	v_cmp_gt_f32_e32 vcc, s50, v139
	v_mul_f32_e32 v154, 0x4b800000, v139
	s_nop 0
	v_cndmask_b32_e32 v139, v139, v154, vcc
	v_rsq_f32_e32 v139, v139
	s_nop 0
	v_mul_f32_e32 v154, 0x45800000, v139
	v_cndmask_b32_e32 v154, v139, v154, vcc
	v_pk_mul_f32 v[120:121], v[120:121], v[154:155] op_sel_hi:[1,0]
	v_pk_mul_f32 v[122:123], v[122:123], v[154:155] op_sel_hi:[1,0]
	v_pk_mul_f32 v[156:157], v[126:127], v[154:155] op_sel_hi:[1,0]
	v_pk_mul_f32 v[126:127], v[124:125], v[154:155] op_sel_hi:[1,0]
	v_cvt_pk_bf16_f32 v124, v120, v121
	v_mov_b64_e32 v[120:121], s[16:17]
	v_cvt_pk_bf16_f32 v125, v122, v123
	v_cvt_pk_bf16_f32 v126, v126, v127
	v_cvt_pk_bf16_f32 v127, v156, v157
	v_mad_i64_i32 v[156:157], s[26:27], v138, s93, v[120:121]
	v_lshlrev_b64 v[122:123], 1, v[158:159]
	v_lshl_add_u64 v[156:157], v[156:157], 0, v[122:123]
	global_store_dwordx4 v[156:157], v[124:127], off
	s_nop 1
	v_pk_mul_f32 v[118:119], v[118:119], v[154:155] op_sel_hi:[1,0]
	v_pk_mul_f32 v[116:117], v[116:117], v[154:155] op_sel_hi:[1,0]
	v_pk_mul_f32 v[124:125], v[114:115], v[154:155] op_sel_hi:[1,0]
	v_pk_mul_f32 v[114:115], v[112:113], v[154:155] op_sel_hi:[1,0]
	v_cvt_pk_bf16_f32 v112, v116, v117
	v_cvt_pk_bf16_f32 v113, v118, v119
	v_cvt_pk_bf16_f32 v114, v114, v115
	v_cvt_pk_bf16_f32 v115, v124, v125
	global_store_dwordx4 v[156:157], v[112:115], off offset:256
	s_nop 1
	v_or_b32_e32 v116, 16, v138
	v_ashrrev_i32_e32 v117, 31, v116
	v_lshl_add_u64 v[112:113], v[116:117], 4, s[28:29]
	v_mov_b32_e32 v112, v186
	v_mov_b32_e32 v113, v187
	v_mov_b32_e32 v114, v188
	v_mov_b32_e32 v115, v189
	v_mov_b32_e32 v118, v113
	v_mov_b32_e32 v119, v114
	v_mov_b32_e32 v113, v115
	v_pk_add_f32 v[112:113], v[118:119], v[112:113]
	s_nop 0
	v_add_f32_e32 v112, v112, v113
	v_fmamk_f32 v112, v112, 0x3b800000, v171
	v_cmp_gt_f32_e32 vcc, s50, v112
	v_mul_f32_e32 v113, 0x4b800000, v112
	s_nop 0
	v_cndmask_b32_e32 v112, v112, v113, vcc
	v_rsq_f32_e32 v112, v112
	s_nop 0
	v_mul_f32_e32 v113, 0x45800000, v112
	v_cndmask_b32_e32 v112, v112, v113, vcc
	v_pk_mul_f32 v[108:109], v[108:109], v[112:113] op_sel_hi:[1,0]
	v_pk_mul_f32 v[110:111], v[110:111], v[112:113] op_sel_hi:[1,0]
	v_pk_mul_f32 v[114:115], v[106:107], v[112:113] op_sel_hi:[1,0]
	v_pk_mul_f32 v[106:107], v[104:105], v[112:113] op_sel_hi:[1,0]
	v_cvt_pk_bf16_f32 v104, v108, v109
	v_mad_i64_i32 v[108:109], s[26:27], v116, s93, v[120:121]
	v_cvt_pk_bf16_f32 v105, v110, v111
	v_cvt_pk_bf16_f32 v106, v106, v107
	v_cvt_pk_bf16_f32 v107, v114, v115
	v_lshl_add_u64 v[108:109], v[108:109], 0, v[122:123]
	global_store_dwordx4 v[108:109], v[104:107], off
	s_nop 1
	v_pk_mul_f32 v[102:103], v[102:103], v[112:113] op_sel_hi:[1,0]
	v_pk_mul_f32 v[100:101], v[100:101], v[112:113] op_sel_hi:[1,0]
	v_pk_mul_f32 v[104:105], v[98:99], v[112:113] op_sel_hi:[1,0]
	v_pk_mul_f32 v[98:99], v[96:97], v[112:113] op_sel_hi:[1,0]
	v_cvt_pk_bf16_f32 v96, v100, v101
	v_cvt_pk_bf16_f32 v97, v102, v103
	v_cvt_pk_bf16_f32 v98, v98, v99
	v_cvt_pk_bf16_f32 v99, v104, v105
	global_store_dwordx4 v[108:109], v[96:99], off offset:256
	s_nop 1
	v_or_b32_e32 v100, 32, v138
	v_ashrrev_i32_e32 v101, 31, v100
	v_lshl_add_u64 v[96:97], v[100:101], 4, s[28:29]
	v_mov_b32_e32 v96, v190
	v_mov_b32_e32 v97, v191
	v_mov_b32_e32 v98, v192
	v_mov_b32_e32 v99, v193
	v_mov_b32_e32 v102, v97
	v_mov_b32_e32 v103, v98
	v_mov_b32_e32 v97, v99
	v_pk_add_f32 v[96:97], v[102:103], v[96:97]
	s_nop 0
	v_add_f32_e32 v96, v96, v97
	v_fmamk_f32 v96, v96, 0x3b800000, v171
	v_cmp_gt_f32_e32 vcc, s50, v96
	v_mul_f32_e32 v97, 0x4b800000, v96
	s_nop 0
	v_cndmask_b32_e32 v96, v96, v97, vcc
	v_rsq_f32_e32 v96, v96
	s_nop 0
	v_mul_f32_e32 v97, 0x45800000, v96
	v_cndmask_b32_e32 v96, v96, v97, vcc
	v_pk_mul_f32 v[92:93], v[92:93], v[96:97] op_sel_hi:[1,0]
	v_pk_mul_f32 v[94:95], v[94:95], v[96:97] op_sel_hi:[1,0]
	v_pk_mul_f32 v[98:99], v[90:91], v[96:97] op_sel_hi:[1,0]
	v_pk_mul_f32 v[90:91], v[88:89], v[96:97] op_sel_hi:[1,0]
	v_cvt_pk_bf16_f32 v88, v92, v93
	v_mad_i64_i32 v[92:93], s[26:27], v100, s93, v[120:121]
	v_cvt_pk_bf16_f32 v89, v94, v95
	v_cvt_pk_bf16_f32 v90, v90, v91
	v_cvt_pk_bf16_f32 v91, v98, v99
	v_lshl_add_u64 v[92:93], v[92:93], 0, v[122:123]
	global_store_dwordx4 v[92:93], v[88:91], off
	s_nop 1
	v_pk_mul_f32 v[86:87], v[86:87], v[96:97] op_sel_hi:[1,0]
	v_pk_mul_f32 v[84:85], v[84:85], v[96:97] op_sel_hi:[1,0]
	v_pk_mul_f32 v[88:89], v[82:83], v[96:97] op_sel_hi:[1,0]
	v_pk_mul_f32 v[82:83], v[80:81], v[96:97] op_sel_hi:[1,0]
	v_cvt_pk_bf16_f32 v80, v84, v85
	v_cvt_pk_bf16_f32 v81, v86, v87
	v_cvt_pk_bf16_f32 v82, v82, v83
	v_cvt_pk_bf16_f32 v83, v88, v89
	global_store_dwordx4 v[92:93], v[80:83], off offset:256
	s_nop 1
	v_or_b32_e32 v84, 48, v138
	v_ashrrev_i32_e32 v85, 31, v84
	v_lshl_add_u64 v[80:81], v[84:85], 4, s[28:29]
	v_mov_b32_e32 v80, v194
	v_mov_b32_e32 v81, v195
	v_mov_b32_e32 v82, v196
	v_mov_b32_e32 v83, v197
	v_mov_b32_e32 v86, v81
	v_mov_b32_e32 v87, v82
	v_mov_b32_e32 v81, v83
	v_pk_add_f32 v[80:81], v[86:87], v[80:81]
	s_nop 0
	v_add_f32_e32 v80, v80, v81
	v_fmamk_f32 v80, v80, 0x3b800000, v171
	v_cmp_gt_f32_e32 vcc, s50, v80
	v_mul_f32_e32 v81, 0x4b800000, v80
	s_nop 0
	v_cndmask_b32_e32 v80, v80, v81, vcc
	v_rsq_f32_e32 v80, v80
	s_nop 0
	v_mul_f32_e32 v81, 0x45800000, v80
	v_cndmask_b32_e32 v80, v80, v81, vcc
	v_pk_mul_f32 v[76:77], v[76:77], v[80:81] op_sel_hi:[1,0]
	v_pk_mul_f32 v[78:79], v[78:79], v[80:81] op_sel_hi:[1,0]
	v_pk_mul_f32 v[82:83], v[74:75], v[80:81] op_sel_hi:[1,0]
	v_pk_mul_f32 v[74:75], v[72:73], v[80:81] op_sel_hi:[1,0]
	v_cvt_pk_bf16_f32 v72, v76, v77
	v_mad_i64_i32 v[76:77], s[26:27], v84, s93, v[120:121]
	v_cvt_pk_bf16_f32 v73, v78, v79
	v_cvt_pk_bf16_f32 v74, v74, v75
	v_cvt_pk_bf16_f32 v75, v82, v83
	v_lshl_add_u64 v[76:77], v[76:77], 0, v[122:123]
	global_store_dwordx4 v[76:77], v[72:75], off
	s_nop 1
	v_pk_mul_f32 v[70:71], v[70:71], v[80:81] op_sel_hi:[1,0]
	v_pk_mul_f32 v[68:69], v[68:69], v[80:81] op_sel_hi:[1,0]
	v_pk_mul_f32 v[72:73], v[66:67], v[80:81] op_sel_hi:[1,0]
	v_pk_mul_f32 v[66:67], v[64:65], v[80:81] op_sel_hi:[1,0]
	v_cvt_pk_bf16_f32 v64, v68, v69
	v_cvt_pk_bf16_f32 v65, v70, v71
	v_cvt_pk_bf16_f32 v66, v66, v67
	v_cvt_pk_bf16_f32 v67, v72, v73
	global_store_dwordx4 v[76:77], v[64:67], off offset:256
	s_nop 1
	v_add_u32_e32 v68, 0x80, v138
	v_ashrrev_i32_e32 v69, 31, v68
	v_lshl_add_u64 v[64:65], v[68:69], 4, s[28:29]
	v_mov_b32_e32 v64, v198
	v_mov_b32_e32 v65, v199
	v_mov_b32_e32 v66, v200
	v_mov_b32_e32 v67, v201
	v_mov_b32_e32 v70, v65
	v_mov_b32_e32 v71, v66
	v_mov_b32_e32 v65, v67
	v_pk_add_f32 v[64:65], v[70:71], v[64:65]
	s_nop 0
	v_add_f32_e32 v64, v64, v65
	v_fmamk_f32 v64, v64, 0x3b800000, v171
	v_cmp_gt_f32_e32 vcc, s50, v64
	v_mul_f32_e32 v65, 0x4b800000, v64
	s_nop 0
	v_cndmask_b32_e32 v64, v64, v65, vcc
	v_rsq_f32_e32 v64, v64
	s_nop 0
	v_mul_f32_e32 v65, 0x45800000, v64
	v_cndmask_b32_e32 v64, v64, v65, vcc
	v_pk_mul_f32 v[60:61], v[60:61], v[64:65] op_sel_hi:[1,0]
	v_pk_mul_f32 v[62:63], v[62:63], v[64:65] op_sel_hi:[1,0]
	v_pk_mul_f32 v[66:67], v[58:59], v[64:65] op_sel_hi:[1,0]
	v_pk_mul_f32 v[58:59], v[56:57], v[64:65] op_sel_hi:[1,0]
	v_cvt_pk_bf16_f32 v56, v60, v61
	v_mad_i64_i32 v[60:61], s[26:27], v68, s93, v[120:121]
	v_cvt_pk_bf16_f32 v57, v62, v63
	v_cvt_pk_bf16_f32 v58, v58, v59
	v_cvt_pk_bf16_f32 v59, v66, v67
	v_lshl_add_u64 v[60:61], v[60:61], 0, v[122:123]
	global_store_dwordx4 v[60:61], v[56:59], off
	s_nop 1
	v_pk_mul_f32 v[54:55], v[54:55], v[64:65] op_sel_hi:[1,0]
	v_pk_mul_f32 v[52:53], v[52:53], v[64:65] op_sel_hi:[1,0]
	v_pk_mul_f32 v[56:57], v[50:51], v[64:65] op_sel_hi:[1,0]
	v_pk_mul_f32 v[50:51], v[48:49], v[64:65] op_sel_hi:[1,0]
	v_cvt_pk_bf16_f32 v48, v52, v53
	v_cvt_pk_bf16_f32 v49, v54, v55
	v_cvt_pk_bf16_f32 v50, v50, v51
	v_cvt_pk_bf16_f32 v51, v56, v57
	global_store_dwordx4 v[60:61], v[48:51], off offset:256
	s_nop 1
	v_add_u32_e32 v52, 0x90, v138
	v_ashrrev_i32_e32 v53, 31, v52
	v_lshl_add_u64 v[48:49], v[52:53], 4, s[28:29]
	v_mov_b32_e32 v48, v202
	v_mov_b32_e32 v49, v203
	v_mov_b32_e32 v50, v204
	v_mov_b32_e32 v51, v205
	v_mov_b32_e32 v54, v49
	v_mov_b32_e32 v55, v50
	v_mov_b32_e32 v49, v51
	v_pk_add_f32 v[48:49], v[54:55], v[48:49]
	s_nop 0
	v_add_f32_e32 v48, v48, v49
	v_fmamk_f32 v48, v48, 0x3b800000, v171
	v_cmp_gt_f32_e32 vcc, s50, v48
	v_mul_f32_e32 v49, 0x4b800000, v48
	s_nop 0
	v_cndmask_b32_e32 v48, v48, v49, vcc
	v_rsq_f32_e32 v48, v48
	s_nop 0
	v_mul_f32_e32 v49, 0x45800000, v48
	v_cndmask_b32_e32 v48, v48, v49, vcc
	v_pk_mul_f32 v[44:45], v[44:45], v[48:49] op_sel_hi:[1,0]
	v_pk_mul_f32 v[46:47], v[46:47], v[48:49] op_sel_hi:[1,0]
	v_pk_mul_f32 v[50:51], v[42:43], v[48:49] op_sel_hi:[1,0]
	v_pk_mul_f32 v[42:43], v[40:41], v[48:49] op_sel_hi:[1,0]
	v_cvt_pk_bf16_f32 v40, v44, v45
	v_mad_i64_i32 v[44:45], s[26:27], v52, s93, v[120:121]
	v_cvt_pk_bf16_f32 v41, v46, v47
	v_cvt_pk_bf16_f32 v42, v42, v43
	v_cvt_pk_bf16_f32 v43, v50, v51
	v_lshl_add_u64 v[44:45], v[44:45], 0, v[122:123]
	global_store_dwordx4 v[44:45], v[40:43], off
	s_nop 1
	v_pk_mul_f32 v[38:39], v[38:39], v[48:49] op_sel_hi:[1,0]
	v_pk_mul_f32 v[36:37], v[36:37], v[48:49] op_sel_hi:[1,0]
	v_pk_mul_f32 v[40:41], v[34:35], v[48:49] op_sel_hi:[1,0]
	v_pk_mul_f32 v[34:35], v[32:33], v[48:49] op_sel_hi:[1,0]
	v_cvt_pk_bf16_f32 v32, v36, v37
	v_cvt_pk_bf16_f32 v33, v38, v39
	v_cvt_pk_bf16_f32 v34, v34, v35
	v_cvt_pk_bf16_f32 v35, v40, v41
	global_store_dwordx4 v[44:45], v[32:35], off offset:256
	s_nop 1
	v_add_u32_e32 v36, 0xa0, v138
	v_ashrrev_i32_e32 v37, 31, v36
	v_lshl_add_u64 v[32:33], v[36:37], 4, s[28:29]
	v_mov_b32_e32 v32, v206
	v_mov_b32_e32 v33, v207
	v_mov_b32_e32 v34, v208
	v_mov_b32_e32 v35, v209
	v_mov_b32_e32 v38, v33
	v_mov_b32_e32 v39, v34
	v_mov_b32_e32 v33, v35
	v_pk_add_f32 v[32:33], v[38:39], v[32:33]
	s_nop 0
	v_add_f32_e32 v32, v32, v33
	v_fmamk_f32 v32, v32, 0x3b800000, v171
	v_cmp_gt_f32_e32 vcc, s50, v32
	v_mul_f32_e32 v33, 0x4b800000, v32
	s_nop 0
	v_cndmask_b32_e32 v32, v32, v33, vcc
	v_rsq_f32_e32 v32, v32
	s_nop 0
	v_mul_f32_e32 v33, 0x45800000, v32
	v_cndmask_b32_e32 v32, v32, v33, vcc
	v_pk_mul_f32 v[28:29], v[28:29], v[32:33] op_sel_hi:[1,0]
	v_pk_mul_f32 v[30:31], v[30:31], v[32:33] op_sel_hi:[1,0]
	v_pk_mul_f32 v[34:35], v[26:27], v[32:33] op_sel_hi:[1,0]
	v_pk_mul_f32 v[26:27], v[24:25], v[32:33] op_sel_hi:[1,0]
	v_cvt_pk_bf16_f32 v24, v28, v29
	v_mad_i64_i32 v[28:29], s[26:27], v36, s93, v[120:121]
	v_cvt_pk_bf16_f32 v25, v30, v31
	v_cvt_pk_bf16_f32 v26, v26, v27
	v_cvt_pk_bf16_f32 v27, v34, v35
	v_lshl_add_u64 v[28:29], v[28:29], 0, v[122:123]
	global_store_dwordx4 v[28:29], v[24:27], off
	s_nop 1
	v_pk_mul_f32 v[22:23], v[22:23], v[32:33] op_sel_hi:[1,0]
	v_pk_mul_f32 v[20:21], v[20:21], v[32:33] op_sel_hi:[1,0]
	v_pk_mul_f32 v[24:25], v[18:19], v[32:33] op_sel_hi:[1,0]
	v_pk_mul_f32 v[18:19], v[16:17], v[32:33] op_sel_hi:[1,0]
	v_cvt_pk_bf16_f32 v16, v20, v21
	v_cvt_pk_bf16_f32 v17, v22, v23
	v_cvt_pk_bf16_f32 v18, v18, v19
	v_cvt_pk_bf16_f32 v19, v24, v25
	global_store_dwordx4 v[28:29], v[16:19], off offset:256
	s_nop 1
	v_add_u32_e32 v20, 0xb0, v138
	v_ashrrev_i32_e32 v21, 31, v20
	v_lshl_add_u64 v[16:17], v[20:21], 4, s[28:29]
	s_and_b64 vcc, exec, s[2:3]
	v_mov_b32_e32 v16, v210
	v_mov_b32_e32 v17, v211
	v_mov_b32_e32 v18, v212
	v_mov_b32_e32 v19, v213
	v_mov_b32_e32 v22, v17
	v_mov_b32_e32 v23, v18
	v_mov_b32_e32 v17, v19
	v_pk_add_f32 v[16:17], v[22:23], v[16:17]
	s_nop 0
	v_add_f32_e32 v16, v16, v17
	v_fmamk_f32 v16, v16, 0x3b800000, v171
	v_mul_f32_e32 v17, 0x4b800000, v16
	v_cmp_gt_f32_e64 s[2:3], s50, v16
	s_nop 1
	v_cndmask_b32_e64 v16, v16, v17, s[2:3]
	v_rsq_f32_e32 v18, v16
	v_mad_i64_i32 v[16:17], s[26:27], v20, s93, v[120:121]
	v_lshl_add_u64 v[16:17], v[16:17], 0, v[122:123]
	v_mul_f32_e32 v19, 0x45800000, v18
	v_cndmask_b32_e64 v18, v18, v19, s[2:3]
	v_pk_mul_f32 v[14:15], v[14:15], v[18:19] op_sel_hi:[1,0]
	v_pk_mul_f32 v[12:13], v[12:13], v[18:19] op_sel_hi:[1,0]
	v_pk_mul_f32 v[10:11], v[10:11], v[18:19] op_sel_hi:[1,0]
	v_pk_mul_f32 v[8:9], v[8:9], v[18:19] op_sel_hi:[1,0]
	v_pk_mul_f32 v[6:7], v[6:7], v[18:19] op_sel_hi:[1,0]
	v_pk_mul_f32 v[4:5], v[4:5], v[18:19] op_sel_hi:[1,0]
	v_pk_mul_f32 v[20:21], v[2:3], v[18:19] op_sel_hi:[1,0]
	v_pk_mul_f32 v[18:19], v[0:1], v[18:19] op_sel_hi:[1,0]
	v_cvt_pk_bf16_f32 v0, v12, v13
	v_cvt_pk_bf16_f32 v1, v14, v15
	v_cvt_pk_bf16_f32 v2, v8, v9
	v_cvt_pk_bf16_f32 v3, v10, v11
	s_mov_b64 s[2:3], -1
	v_cvt_pk_bf16_f32 v4, v4, v5
	v_cvt_pk_bf16_f32 v5, v6, v7
	v_cvt_pk_bf16_f32 v6, v18, v19
	v_cvt_pk_bf16_f32 v7, v20, v21
	global_store_dwordx4 v[16:17], v[0:3], off
	s_nop 1
	global_store_dwordx4 v[16:17], v[4:7], off offset:256
	s_nop 1
	s_cbranch_vccnz .LBB0_1052
	s_andn2_b64 vcc, exec, s[14:15]
	s_cbranch_vccnz .LBB0_1051
	s_barrier
	s_branch .LBB0_1051

; __device__ __forceinline__ float rstd4(const float* pp, int row, float invn) { const f32x4 a = *(const f32x4*)(pp + (size_t)row * 4); return rsqrtf(((a.x + a.y) + (a.z + a.w)) * invn + 1e-6f); }
.LBB0_1097:
	s_lshl_b32 s33, s45, 8
	s_add_i32 s33, s33, s92
	s_ashr_i32 s4, s33, 8
	s_lshl_b32 s50, s44, 1
	v_or_b32_e32 v154, s33, v137
	s_and_b32 s14, s4, -8
	v_readlane_b32 s4, v254, 12
	v_ashrrev_i32_e32 v155, 31, v154
	v_readlane_b32 s5, v254, 13
	s_nop 1
	v_lshl_add_u64 v[156:157], v[154:155], 4, s[4:5]
	v_mov_b32_e32 v218, v154
	v_ashrrev_i32_e32 v219, 31, v218
	v_lshl_add_u64 v[218:219], v[218:219], 4, s[4:5]
	global_load_dwordx4 v[186:189], v[218:219], off
	v_add_u32_e32 v218, 16, v154
	v_ashrrev_i32_e32 v219, 31, v218
	v_lshl_add_u64 v[218:219], v[218:219], 4, s[4:5]
	global_load_dwordx4 v[190:193], v[218:219], off
	v_add_u32_e32 v218, 32, v154
	v_ashrrev_i32_e32 v219, 31, v218
	v_lshl_add_u64 v[218:219], v[218:219], 4, s[4:5]
	global_load_dwordx4 v[194:197], v[218:219], off
	v_add_u32_e32 v218, 48, v154
	v_ashrrev_i32_e32 v219, 31, v218
	v_lshl_add_u64 v[218:219], v[218:219], 4, s[4:5]
	global_load_dwordx4 v[198:201], v[218:219], off
	v_add_u32_e32 v218, 128, v154
	v_ashrrev_i32_e32 v219, 31, v218
	v_lshl_add_u64 v[218:219], v[218:219], 4, s[4:5]
	global_load_dwordx4 v[202:205], v[218:219], off
	v_add_u32_e32 v218, 144, v154
	v_ashrrev_i32_e32 v219, 31, v218
	v_lshl_add_u64 v[218:219], v[218:219], 4, s[4:5]
	global_load_dwordx4 v[206:209], v[218:219], off
	v_add_u32_e32 v218, 160, v154
	v_ashrrev_i32_e32 v219, 31, v218
	v_lshl_add_u64 v[218:219], v[218:219], 4, s[4:5]
	global_load_dwordx4 v[210:213], v[218:219], off
	v_add_u32_e32 v218, 176, v154
	v_ashrrev_i32_e32 v219, 31, v218
	v_lshl_add_u64 v[218:219], v[218:219], 4, s[4:5]
	global_load_dwordx4 v[214:217], v[218:219], off
	s_waitcnt vmcnt(0)
	s_mov_b32 s4, 0x800000
	v_mov_b32_e32 v156, v186
	v_mov_b32_e32 v157, v187
	v_mov_b32_e32 v158, v188
	v_mov_b32_e32 v159, v189
	v_mov_b32_e32 v160, v157
	v_mov_b32_e32 v161, v158
	v_mov_b32_e32 v157, v159
	v_pk_add_f32 v[156:157], v[160:161], v[156:157]
	s_nop 0
	v_add_f32_e32 v144, v156, v157
	v_fmamk_f32 v144, v144, 0x3c000000, v171
	v_cmp_gt_f32_e32 vcc, s4, v144
	v_mul_f32_e32 v155, 0x4b800000, v144
	s_mov_b64 s[4:5], -1
	v_cndmask_b32_e32 v144, v144, v155, vcc
	v_rsq_f32_e32 v144, v144
	s_nop 0
	v_mul_f32_e32 v155, 0x45800000, v144
	v_cndmask_b32_e32 v156, v144, v155, vcc
	v_bitop3_b32 v144, s33, v178, v137 bitop3:0xc8
	v_pk_mul_f32 v[122:123], v[122:123], v[156:157] op_sel_hi:[1,0]
	v_pk_mul_f32 v[158:159], v[120:121], v[156:157] op_sel_hi:[1,0]
	v_pk_mul_f32 v[120:121], v[126:127], v[156:157] op_sel_hi:[1,0]
	v_pk_mul_f32 v[124:125], v[124:125], v[156:157] op_sel_hi:[1,0]
	s_and_b64 vcc, exec, s[24:25]
	v_lshlrev_b32_e32 v126, 1, v144
	s_cbranch_vccz .LBB0_1099
	s_add_i32 s4, s14, s50
	s_ashr_i32 s5, s4, 31
	s_lshl_b64 s[4:5], s[4:5], 18
	v_lshl_add_u64 v[160:161], v[138:139], 0, s[4:5]
	v_mov_b32_e32 v127, v145
	v_lshl_add_u64 v[160:161], v[160:161], 0, v[126:127]
	v_bfe_u32 v127, v158, 16, 1
	v_add3_u32 v127, v158, v127, s1
	global_store_short_d16_hi v[160:161], v127, off
	v_bfe_u32 v127, v159, 16, 1
	v_add_co_u32_e32 v164, vcc, s51, v160
	v_add3_u32 v127, v159, v127, s1
	s_nop 0
	v_addc_co_u32_e32 v165, vcc, 0, v161, vcc
	s_movk_i32 s4, 0x2000
	global_store_short_d16_hi v[164:165], v127, off
	v_bfe_u32 v127, v122, 16, 1
	v_add_co_u32_e32 v164, vcc, s4, v160
	v_add3_u32 v127, v122, v127, s1
	s_nop 0
	v_addc_co_u32_e32 v165, vcc, 0, v161, vcc
	s_movk_i32 s4, 0x3000
	global_store_short_d16_hi v[164:165], v127, off
	v_bfe_u32 v127, v123, 16, 1
	v_add_co_u32_e32 v164, vcc, s4, v160
	v_add3_u32 v127, v123, v127, s1
	s_nop 0
	v_addc_co_u32_e32 v165, vcc, 0, v161, vcc
	s_movk_i32 s4, 0x4000
	global_store_short_d16_hi v[164:165], v127, off
	v_bfe_u32 v127, v124, 16, 1
	v_add_co_u32_e32 v164, vcc, s4, v160
	v_add3_u32 v127, v124, v127, s1
	s_nop 0
	v_addc_co_u32_e32 v165, vcc, 0, v161, vcc
	global_store_short_d16_hi v[164:165], v127, off
	v_bfe_u32 v127, v125, 16, 1
	v_add_co_u32_e32 v164, vcc, 0x5000, v160
	v_add3_u32 v127, v125, v127, s1
	s_nop 0
	v_addc_co_u32_e32 v165, vcc, 0, v161, vcc
	global_store_short_d16_hi v[164:165], v127, off
	v_bfe_u32 v127, v120, 16, 1
	v_add_co_u32_e32 v164, vcc, 0x6000, v160
	v_add3_u32 v127, v120, v127, s1
	s_nop 0
	v_addc_co_u32_e32 v165, vcc, 0, v161, vcc
	global_store_short_d16_hi v[164:165], v127, off
	v_bfe_u32 v127, v121, 16, 1
	v_add_co_u32_e32 v160, vcc, 0x7000, v160
	v_add3_u32 v127, v121, v127, s1
	s_nop 0
	v_addc_co_u32_e32 v161, vcc, 0, v161, vcc
	global_store_short_d16_hi v[160:161], v127, off
	s_mov_b64 s[4:5], 0
.LBB0_1099:
	v_mad_i64_i32 v[160:161], s[30:31], v154, s93, 0
	s_andn2_b64 vcc, exec, s[4:5]
	v_lshl_add_u64 v[160:161], s[16:17], 0, v[160:161]
	s_mul_i32 s30, s44, 0xc0
	v_lshlrev_b32_e32 v144, 1, v136
	s_cbranch_vccnz .LBB0_1101
	s_ashr_i32 s31, s30, 31
	v_cvt_pk_bf16_f32 v167, v120, v121
	v_lshl_add_u64 v[120:121], s[30:31], 1, v[160:161]
	v_cvt_pk_bf16_f32 v164, v158, v159
	v_cvt_pk_bf16_f32 v165, v122, v123
	v_cvt_pk_bf16_f32 v166, v124, v125
	v_lshl_add_u64 v[120:121], v[120:121], 0, v[144:145]
	global_store_dwordx4 v[120:121], v[164:167], off
	s_nop 1
.LBB0_1101:
	v_mov_b32_e32 v120, v156
	v_mov_b32_e32 v121, v156
	v_mov_b32_e32 v157, v156
	v_pk_mul_f32 v[118:119], v[118:119], v[120:121]
	v_pk_mul_f32 v[114:115], v[114:115], v[120:121]
	v_cndmask_b32_e64 v120, 0, 1, s[24:25]
	s_or_b32 s51, s50, 1
	v_pk_mul_f32 v[116:117], v[116:117], v[156:157]
	v_pk_mul_f32 v[112:113], v[112:113], v[156:157]
	v_cmp_ne_u32_e64 s[4:5], 1, v120
	s_andn2_b64 vcc, exec, s[24:25]
	s_mov_b64 s[34:35], -1
	s_cbranch_vccnz .LBB0_1103
	s_add_i32 s34, s14, s51
	s_ashr_i32 s35, s34, 31
	s_lshl_b64 s[34:35], s[34:35], 18
	v_lshl_add_u64 v[120:121], v[138:139], 0, s[34:35]
	v_mov_b32_e32 v127, v145
	v_bfe_u32 v122, v116, 16, 1
	v_lshl_add_u64 v[120:121], v[120:121], 0, v[126:127]
	v_add3_u32 v122, v116, v122, s1
	global_store_short_d16_hi v[120:121], v122, off
	v_bfe_u32 v122, v117, 16, 1
	s_movk_i32 s15, 0x1000
	v_add3_u32 v124, v117, v122, s1
	v_add_co_u32_e32 v122, vcc, s15, v120
	s_movk_i32 s15, 0x2000
	s_nop 0
	v_addc_co_u32_e32 v123, vcc, 0, v121, vcc
	global_store_short_d16_hi v[122:123], v124, off
	v_bfe_u32 v122, v118, 16, 1
	v_add3_u32 v124, v118, v122, s1
	v_add_co_u32_e32 v122, vcc, s15, v120
	s_movk_i32 s15, 0x3000
	s_nop 0
	v_addc_co_u32_e32 v123, vcc, 0, v121, vcc
	global_store_short_d16_hi v[122:123], v124, off
	v_bfe_u32 v122, v119, 16, 1
	v_add3_u32 v124, v119, v122, s1
	v_add_co_u32_e32 v122, vcc, s15, v120
	s_movk_i32 s15, 0x4000
	s_nop 0
	v_addc_co_u32_e32 v123, vcc, 0, v121, vcc
	global_store_short_d16_hi v[122:123], v124, off
	v_bfe_u32 v122, v112, 16, 1
	v_add3_u32 v124, v112, v122, s1
	v_add_co_u32_e32 v122, vcc, s15, v120
	s_mov_b64 s[34:35], 0
	s_nop 0
	v_addc_co_u32_e32 v123, vcc, 0, v121, vcc
	global_store_short_d16_hi v[122:123], v124, off
	v_bfe_u32 v122, v113, 16, 1
	v_add3_u32 v124, v113, v122, s1
	v_add_co_u32_e32 v122, vcc, 0x5000, v120
	s_nop 1
	v_addc_co_u32_e32 v123, vcc, 0, v121, vcc
	global_store_short_d16_hi v[122:123], v124, off
	v_bfe_u32 v122, v114, 16, 1
	v_add3_u32 v124, v114, v122, s1
	v_add_co_u32_e32 v122, vcc, 0x6000, v120
	s_nop 1
	v_addc_co_u32_e32 v123, vcc, 0, v121, vcc
	global_store_short_d16_hi v[122:123], v124, off
	v_bfe_u32 v122, v115, 16, 1
	v_add_co_u32_e32 v120, vcc, 0x7000, v120
	v_add3_u32 v122, v115, v122, s1
	s_nop 0
	v_addc_co_u32_e32 v121, vcc, 0, v121, vcc
	global_store_short_d16_hi v[120:121], v122, off
.LBB0_1103:
	s_andn2_b64 vcc, exec, s[34:35]
	s_mul_i32 s34, s51, 0x60
	s_cbranch_vccnz .LBB0_1105
	s_ashr_i32 s35, s34, 31
	v_cvt_pk_bf16_f32 v116, v116, v117
	v_cvt_pk_bf16_f32 v117, v118, v119
	v_cvt_pk_bf16_f32 v118, v112, v113
	v_lshl_add_u64 v[112:113], s[34:35], 1, v[160:161]
	v_cvt_pk_bf16_f32 v119, v114, v115
	v_lshl_add_u64 v[112:113], v[112:113], 0, v[144:145]
	global_store_dwordx4 v[112:113], v[116:119], off
	s_nop 1
.LBB0_1105:
	v_or_b32_e32 v114, 16, v154
	v_readlane_b32 s44, v254, 12
	v_ashrrev_i32_e32 v115, 31, v114
	v_readlane_b32 s45, v254, 13
	s_mov_b32 s15, 0x800000
	s_nop 0
	v_lshl_add_u64 v[112:113], v[114:115], 4, s[44:45]
	s_mov_b64 s[44:45], -1
	v_mov_b32_e32 v116, v190
	v_mov_b32_e32 v117, v191
	v_mov_b32_e32 v118, v192
	v_mov_b32_e32 v119, v193
	v_mov_b32_e32 v112, v117
	v_mov_b32_e32 v113, v118
	v_mov_b32_e32 v117, v119
	v_pk_add_f32 v[112:113], v[112:113], v[116:117]
	s_nop 0
	v_add_f32_e32 v112, v112, v113
	v_fmamk_f32 v112, v112, 0x3c000000, v171
	v_cmp_gt_f32_e32 vcc, s15, v112
	v_mul_f32_e32 v113, 0x4b800000, v112
	s_movk_i32 s15, 0x7df
	v_cndmask_b32_e32 v112, v112, v113, vcc
	v_rsq_f32_e32 v112, v112
	s_nop 0
	v_mul_f32_e32 v113, 0x45800000, v112
	v_cndmask_b32_e32 v112, v112, v113, vcc
	v_bitop3_b32 v113, v154, s15, 16 bitop3:0xc8
	v_pk_mul_f32 v[110:111], v[110:111], v[112:113] op_sel_hi:[1,0]
	v_pk_mul_f32 v[108:109], v[108:109], v[112:113] op_sel_hi:[1,0]
	v_pk_mul_f32 v[106:107], v[106:107], v[112:113] op_sel_hi:[1,0]
	v_pk_mul_f32 v[104:105], v[104:105], v[112:113] op_sel_hi:[1,0]
	s_and_b64 vcc, exec, s[4:5]
	v_lshlrev_b32_e32 v116, 1, v113
	s_cbranch_vccnz .LBB0_1107
	s_add_i32 s44, s14, s50
	s_ashr_i32 s45, s44, 31
	s_lshl_b64 s[44:45], s[44:45], 18
	v_lshl_add_u64 v[118:119], v[138:139], 0, s[44:45]
	v_mov_b32_e32 v117, v145
	v_bfe_u32 v113, v108, 16, 1
	v_lshl_add_u64 v[118:119], v[118:119], 0, v[116:117]
	v_add3_u32 v113, v108, v113, s1
	s_movk_i32 s15, 0x1000
	global_store_short_d16_hi v[118:119], v113, off
	v_bfe_u32 v113, v109, 16, 1
	v_add_co_u32_e32 v120, vcc, s15, v118
	v_add3_u32 v113, v109, v113, s1
	s_nop 0
	v_addc_co_u32_e32 v121, vcc, 0, v119, vcc
	s_movk_i32 s15, 0x2000
	global_store_short_d16_hi v[120:121], v113, off
	v_bfe_u32 v113, v110, 16, 1
	v_add_co_u32_e32 v120, vcc, s15, v118
	v_add3_u32 v113, v110, v113, s1
	s_nop 0
	v_addc_co_u32_e32 v121, vcc, 0, v119, vcc
	s_movk_i32 s15, 0x3000
	global_store_short_d16_hi v[120:121], v113, off
	v_bfe_u32 v113, v111, 16, 1
	v_add_co_u32_e32 v120, vcc, s15, v118
	v_add3_u32 v113, v111, v113, s1
	s_nop 0
	v_addc_co_u32_e32 v121, vcc, 0, v119, vcc
	s_movk_i32 s15, 0x4000
	global_store_short_d16_hi v[120:121], v113, off
	v_bfe_u32 v113, v104, 16, 1
	v_add_co_u32_e32 v120, vcc, s15, v118
	v_add3_u32 v113, v104, v113, s1
	s_nop 0
	v_addc_co_u32_e32 v121, vcc, 0, v119, vcc
	global_store_short_d16_hi v[120:121], v113, off
	v_bfe_u32 v113, v105, 16, 1
	v_add_co_u32_e32 v120, vcc, 0x5000, v118
	v_add3_u32 v113, v105, v113, s1
	s_nop 0
	v_addc_co_u32_e32 v121, vcc, 0, v119, vcc
	global_store_short_d16_hi v[120:121], v113, off
	v_bfe_u32 v113, v106, 16, 1
	v_add_co_u32_e32 v120, vcc, 0x6000, v118
	v_add3_u32 v113, v106, v113, s1
	s_nop 0
	v_addc_co_u32_e32 v121, vcc, 0, v119, vcc
	global_store_short_d16_hi v[120:121], v113, off
	v_bfe_u32 v113, v107, 16, 1
	v_add_co_u32_e32 v118, vcc, 0x7000, v118
	v_add3_u32 v113, v107, v113, s1
	s_nop 0
	v_addc_co_u32_e32 v119, vcc, 0, v119, vcc
	s_mov_b64 s[44:45], 0
	global_store_short_d16_hi v[118:119], v113, off
.LBB0_1107:
	v_mad_i64_i32 v[114:115], vcc, v114, s93, 0
	s_andn2_b64 vcc, exec, s[44:45]
	v_lshl_add_u64 v[114:115], s[16:17], 0, v[114:115]
	s_cbranch_vccnz .LBB0_1109
	s_ashr_i32 s31, s30, 31
	v_cvt_pk_bf16_f32 v108, v108, v109
	v_cvt_pk_bf16_f32 v109, v110, v111
	v_cvt_pk_bf16_f32 v110, v104, v105
	v_lshl_add_u64 v[104:105], s[30:31], 1, v[114:115]
	v_cvt_pk_bf16_f32 v111, v106, v107
	v_lshl_add_u64 v[104:105], v[104:105], 0, v[144:145]
	global_store_dwordx4 v[104:105], v[108:111], off
	s_nop 1
.LBB0_1109:
	v_mov_b32_e32 v113, v112
	v_mov_b32_e32 v104, v112
	v_mov_b32_e32 v105, v112
	v_pk_mul_f32 v[102:103], v[102:103], v[104:105]
	v_pk_mul_f32 v[100:101], v[100:101], v[112:113]
	v_pk_mul_f32 v[98:99], v[98:99], v[104:105]
	v_pk_mul_f32 v[96:97], v[96:97], v[112:113]
	s_and_b64 vcc, exec, s[4:5]
	s_mov_b64 s[44:45], -1
	s_cbranch_vccnz .LBB0_1111
	s_add_i32 s44, s14, s51
	s_ashr_i32 s45, s44, 31
	s_lshl_b64 s[44:45], s[44:45], 18
	v_lshl_add_u64 v[104:105], v[138:139], 0, s[44:45]
	v_mov_b32_e32 v117, v145
	v_bfe_u32 v106, v100, 16, 1
	v_lshl_add_u64 v[104:105], v[104:105], 0, v[116:117]
	v_add3_u32 v106, v100, v106, s1
	global_store_short_d16_hi v[104:105], v106, off
	v_bfe_u32 v106, v101, 16, 1
	s_movk_i32 s15, 0x1000
	v_add3_u32 v108, v101, v106, s1
	v_add_co_u32_e32 v106, vcc, s15, v104
	s_movk_i32 s15, 0x2000
	s_nop 0
	v_addc_co_u32_e32 v107, vcc, 0, v105, vcc
	global_store_short_d16_hi v[106:107], v108, off
	v_bfe_u32 v106, v102, 16, 1
	v_add3_u32 v108, v102, v106, s1
	v_add_co_u32_e32 v106, vcc, s15, v104
	s_movk_i32 s15, 0x3000
	s_nop 0
	v_addc_co_u32_e32 v107, vcc, 0, v105, vcc
	global_store_short_d16_hi v[106:107], v108, off
	v_bfe_u32 v106, v103, 16, 1
	v_add3_u32 v108, v103, v106, s1
	v_add_co_u32_e32 v106, vcc, s15, v104
	s_movk_i32 s15, 0x4000
	s_nop 0
	v_addc_co_u32_e32 v107, vcc, 0, v105, vcc
	global_store_short_d16_hi v[106:107], v108, off
	v_bfe_u32 v106, v96, 16, 1
	v_add3_u32 v108, v96, v106, s1
	v_add_co_u32_e32 v106, vcc, s15, v104
	s_mov_b64 s[44:45], 0
	s_nop 0
	v_addc_co_u32_e32 v107, vcc, 0, v105, vcc
	global_store_short_d16_hi v[106:107], v108, off
	v_bfe_u32 v106, v97, 16, 1
	v_add3_u32 v108, v97, v106, s1
	v_add_co_u32_e32 v106, vcc, 0x5000, v104
	s_nop 1
	v_addc_co_u32_e32 v107, vcc, 0, v105, vcc
	global_store_short_d16_hi v[106:107], v108, off
	v_bfe_u32 v106, v98, 16, 1
	v_add3_u32 v108, v98, v106, s1
	v_add_co_u32_e32 v106, vcc, 0x6000, v104
	s_nop 1
	v_addc_co_u32_e32 v107, vcc, 0, v105, vcc
	global_store_short_d16_hi v[106:107], v108, off
	v_bfe_u32 v106, v99, 16, 1
	v_add_co_u32_e32 v104, vcc, 0x7000, v104
	v_add3_u32 v106, v99, v106, s1
	s_nop 0
	v_addc_co_u32_e32 v105, vcc, 0, v105, vcc
	global_store_short_d16_hi v[104:105], v106, off
.LBB0_1111:
	s_andn2_b64 vcc, exec, s[44:45]
	s_cbranch_vccnz .LBB0_1113
	s_ashr_i32 s35, s34, 31
	v_cvt_pk_bf16_f32 v100, v100, v101
	v_cvt_pk_bf16_f32 v101, v102, v103
	v_cvt_pk_bf16_f32 v102, v96, v97
	v_lshl_add_u64 v[96:97], s[34:35], 1, v[114:115]
	v_cvt_pk_bf16_f32 v103, v98, v99
	v_lshl_add_u64 v[96:97], v[96:97], 0, v[144:145]
	global_store_dwordx4 v[96:97], v[100:103], off
	s_nop 1
.LBB0_1113:
	v_or_b32_e32 v98, 32, v154
	v_readlane_b32 s44, v254, 12
	v_ashrrev_i32_e32 v99, 31, v98
	v_readlane_b32 s45, v254, 13
	s_mov_b32 s15, 0x800000
	s_nop 0
	v_lshl_add_u64 v[96:97], v[98:99], 4, s[44:45]
	s_mov_b64 s[44:45], -1
	v_mov_b32_e32 v100, v194
	v_mov_b32_e32 v101, v195
	v_mov_b32_e32 v102, v196
	v_mov_b32_e32 v103, v197
	v_mov_b32_e32 v96, v101
	v_mov_b32_e32 v97, v102
	v_mov_b32_e32 v101, v103
	v_pk_add_f32 v[96:97], v[96:97], v[100:101]
	s_nop 0
	v_add_f32_e32 v96, v96, v97
	v_fmamk_f32 v96, v96, 0x3c000000, v171
	v_cmp_gt_f32_e32 vcc, s15, v96
	v_mul_f32_e32 v97, 0x4b800000, v96
	s_movk_i32 s15, 0x7ef
	v_cndmask_b32_e32 v96, v96, v97, vcc
	v_rsq_f32_e32 v96, v96
	s_nop 0
	v_mul_f32_e32 v97, 0x45800000, v96
	v_cndmask_b32_e32 v96, v96, v97, vcc
	v_bitop3_b32 v97, v154, s15, 32 bitop3:0xc8
	v_pk_mul_f32 v[94:95], v[94:95], v[96:97] op_sel_hi:[1,0]
	v_pk_mul_f32 v[92:93], v[92:93], v[96:97] op_sel_hi:[1,0]
	v_pk_mul_f32 v[90:91], v[90:91], v[96:97] op_sel_hi:[1,0]
	v_pk_mul_f32 v[88:89], v[88:89], v[96:97] op_sel_hi:[1,0]
	s_and_b64 vcc, exec, s[4:5]
	v_lshlrev_b32_e32 v100, 1, v97
	s_cbranch_vccnz .LBB0_1115
	s_add_i32 s44, s14, s50
	s_ashr_i32 s45, s44, 31
	s_lshl_b64 s[44:45], s[44:45], 18
	v_lshl_add_u64 v[102:103], v[138:139], 0, s[44:45]
	v_mov_b32_e32 v101, v145
	v_bfe_u32 v97, v92, 16, 1
	v_lshl_add_u64 v[102:103], v[102:103], 0, v[100:101]
	v_add3_u32 v97, v92, v97, s1
	s_movk_i32 s15, 0x1000
	global_store_short_d16_hi v[102:103], v97, off
	v_bfe_u32 v97, v93, 16, 1
	v_add_co_u32_e32 v104, vcc, s15, v102
	v_add3_u32 v97, v93, v97, s1
	s_nop 0
	v_addc_co_u32_e32 v105, vcc, 0, v103, vcc
	s_movk_i32 s15, 0x2000
	global_store_short_d16_hi v[104:105], v97, off
	v_bfe_u32 v97, v94, 16, 1
	v_add_co_u32_e32 v104, vcc, s15, v102
	v_add3_u32 v97, v94, v97, s1
	s_nop 0
	v_addc_co_u32_e32 v105, vcc, 0, v103, vcc
	s_movk_i32 s15, 0x3000
	global_store_short_d16_hi v[104:105], v97, off
	v_bfe_u32 v97, v95, 16, 1
	v_add_co_u32_e32 v104, vcc, s15, v102
	v_add3_u32 v97, v95, v97, s1
	s_nop 0
	v_addc_co_u32_e32 v105, vcc, 0, v103, vcc
	s_movk_i32 s15, 0x4000
	global_store_short_d16_hi v[104:105], v97, off
	v_bfe_u32 v97, v88, 16, 1
	v_add_co_u32_e32 v104, vcc, s15, v102
	v_add3_u32 v97, v88, v97, s1
	s_nop 0
	v_addc_co_u32_e32 v105, vcc, 0, v103, vcc
	global_store_short_d16_hi v[104:105], v97, off
	v_bfe_u32 v97, v89, 16, 1
	v_add_co_u32_e32 v104, vcc, 0x5000, v102
	v_add3_u32 v97, v89, v97, s1
	s_nop 0
	v_addc_co_u32_e32 v105, vcc, 0, v103, vcc
	global_store_short_d16_hi v[104:105], v97, off
	v_bfe_u32 v97, v90, 16, 1
	v_add_co_u32_e32 v104, vcc, 0x6000, v102
	v_add3_u32 v97, v90, v97, s1
	s_nop 0
	v_addc_co_u32_e32 v105, vcc, 0, v103, vcc
	global_store_short_d16_hi v[104:105], v97, off
	v_bfe_u32 v97, v91, 16, 1
	v_add_co_u32_e32 v102, vcc, 0x7000, v102
	v_add3_u32 v97, v91, v97, s1
	s_nop 0
	v_addc_co_u32_e32 v103, vcc, 0, v103, vcc
	s_mov_b64 s[44:45], 0
	global_store_short_d16_hi v[102:103], v97, off
.LBB0_1115:
	v_mad_i64_i32 v[98:99], vcc, v98, s93, 0
	s_andn2_b64 vcc, exec, s[44:45]
	v_lshl_add_u64 v[98:99], s[16:17], 0, v[98:99]
	s_cbranch_vccnz .LBB0_1117
	s_ashr_i32 s31, s30, 31
	v_cvt_pk_bf16_f32 v92, v92, v93
	v_cvt_pk_bf16_f32 v93, v94, v95
	v_cvt_pk_bf16_f32 v94, v88, v89
	v_lshl_add_u64 v[88:89], s[30:31], 1, v[98:99]
	v_cvt_pk_bf16_f32 v95, v90, v91
	v_lshl_add_u64 v[88:89], v[88:89], 0, v[144:145]
	global_store_dwordx4 v[88:89], v[92:95], off
	s_nop 1
.LBB0_1117:
	v_mov_b32_e32 v97, v96
	v_mov_b32_e32 v88, v96
	v_mov_b32_e32 v89, v96
	v_pk_mul_f32 v[86:87], v[86:87], v[88:89]
	v_pk_mul_f32 v[84:85], v[84:85], v[96:97]
	v_pk_mul_f32 v[82:83], v[82:83], v[88:89]
	v_pk_mul_f32 v[80:81], v[80:81], v[96:97]
	s_and_b64 vcc, exec, s[4:5]
	s_mov_b64 s[44:45], -1
	s_cbranch_vccnz .LBB0_1119
	s_add_i32 s44, s14, s51
	s_ashr_i32 s45, s44, 31
	s_lshl_b64 s[44:45], s[44:45], 18
	v_lshl_add_u64 v[88:89], v[138:139], 0, s[44:45]
	v_mov_b32_e32 v101, v145
	v_bfe_u32 v90, v84, 16, 1
	v_lshl_add_u64 v[88:89], v[88:89], 0, v[100:101]
	v_add3_u32 v90, v84, v90, s1
	global_store_short_d16_hi v[88:89], v90, off
	v_bfe_u32 v90, v85, 16, 1
	s_movk_i32 s15, 0x1000
	v_add3_u32 v92, v85, v90, s1
	v_add_co_u32_e32 v90, vcc, s15, v88
	s_movk_i32 s15, 0x2000
	s_nop 0
	v_addc_co_u32_e32 v91, vcc, 0, v89, vcc
	global_store_short_d16_hi v[90:91], v92, off
	v_bfe_u32 v90, v86, 16, 1
	v_add3_u32 v92, v86, v90, s1
	v_add_co_u32_e32 v90, vcc, s15, v88
	s_movk_i32 s15, 0x3000
	s_nop 0
	v_addc_co_u32_e32 v91, vcc, 0, v89, vcc
	global_store_short_d16_hi v[90:91], v92, off
	v_bfe_u32 v90, v87, 16, 1
	v_add3_u32 v92, v87, v90, s1
	v_add_co_u32_e32 v90, vcc, s15, v88
	s_movk_i32 s15, 0x4000
	s_nop 0
	v_addc_co_u32_e32 v91, vcc, 0, v89, vcc
	global_store_short_d16_hi v[90:91], v92, off
	v_bfe_u32 v90, v80, 16, 1
	v_add3_u32 v92, v80, v90, s1
	v_add_co_u32_e32 v90, vcc, s15, v88
	s_mov_b64 s[44:45], 0
	s_nop 0
	v_addc_co_u32_e32 v91, vcc, 0, v89, vcc
	global_store_short_d16_hi v[90:91], v92, off
	v_bfe_u32 v90, v81, 16, 1
	v_add3_u32 v92, v81, v90, s1
	v_add_co_u32_e32 v90, vcc, 0x5000, v88
	s_nop 1
	v_addc_co_u32_e32 v91, vcc, 0, v89, vcc
	global_store_short_d16_hi v[90:91], v92, off
	v_bfe_u32 v90, v82, 16, 1
	v_add3_u32 v92, v82, v90, s1
	v_add_co_u32_e32 v90, vcc, 0x6000, v88
	s_nop 1
	v_addc_co_u32_e32 v91, vcc, 0, v89, vcc
	global_store_short_d16_hi v[90:91], v92, off
	v_bfe_u32 v90, v83, 16, 1
	v_add_co_u32_e32 v88, vcc, 0x7000, v88
	v_add3_u32 v90, v83, v90, s1
	s_nop 0
	v_addc_co_u32_e32 v89, vcc, 0, v89, vcc
	global_store_short_d16_hi v[88:89], v90, off
.LBB0_1119:
	s_andn2_b64 vcc, exec, s[44:45]
	s_cbranch_vccnz .LBB0_1121
	s_ashr_i32 s35, s34, 31
	v_cvt_pk_bf16_f32 v84, v84, v85
	v_cvt_pk_bf16_f32 v85, v86, v87
	v_cvt_pk_bf16_f32 v86, v80, v81
	v_lshl_add_u64 v[80:81], s[34:35], 1, v[98:99]
	v_cvt_pk_bf16_f32 v87, v82, v83
	v_lshl_add_u64 v[80:81], v[80:81], 0, v[144:145]
	global_store_dwordx4 v[80:81], v[84:87], off
	s_nop 1
.LBB0_1121:
	v_or_b32_e32 v82, 48, v154
	v_readlane_b32 s44, v254, 12
	v_ashrrev_i32_e32 v83, 31, v82
	v_readlane_b32 s45, v254, 13
	s_mov_b32 s15, 0x800000
	s_nop 0
	v_lshl_add_u64 v[80:81], v[82:83], 4, s[44:45]
	s_mov_b64 s[44:45], -1
	v_mov_b32_e32 v84, v198
	v_mov_b32_e32 v85, v199
	v_mov_b32_e32 v86, v200
	v_mov_b32_e32 v87, v201
	v_mov_b32_e32 v80, v85
	v_mov_b32_e32 v81, v86
	v_mov_b32_e32 v85, v87
	v_pk_add_f32 v[80:81], v[80:81], v[84:85]
	s_nop 0
	v_add_f32_e32 v80, v80, v81
	v_fmamk_f32 v80, v80, 0x3c000000, v171
	v_cmp_gt_f32_e32 vcc, s15, v80
	v_mul_f32_e32 v81, 0x4b800000, v80
	s_movk_i32 s15, 0x7ff
	v_cndmask_b32_e32 v80, v80, v81, vcc
	v_rsq_f32_e32 v80, v80
	s_nop 0
	v_mul_f32_e32 v81, 0x45800000, v80
	v_cndmask_b32_e32 v80, v80, v81, vcc
	v_bitop3_b32 v81, v154, s15, 48 bitop3:0xc8
	v_pk_mul_f32 v[78:79], v[78:79], v[80:81] op_sel_hi:[1,0]
	v_pk_mul_f32 v[76:77], v[76:77], v[80:81] op_sel_hi:[1,0]
	v_pk_mul_f32 v[74:75], v[74:75], v[80:81] op_sel_hi:[1,0]
	v_pk_mul_f32 v[72:73], v[72:73], v[80:81] op_sel_hi:[1,0]
	s_and_b64 vcc, exec, s[4:5]
	v_lshlrev_b32_e32 v84, 1, v81
	s_cbranch_vccnz .LBB0_1123
	s_add_i32 s44, s14, s50
	s_ashr_i32 s45, s44, 31
	s_lshl_b64 s[44:45], s[44:45], 18
	v_lshl_add_u64 v[86:87], v[138:139], 0, s[44:45]
	v_mov_b32_e32 v85, v145
	v_bfe_u32 v81, v76, 16, 1
	v_lshl_add_u64 v[86:87], v[86:87], 0, v[84:85]
	v_add3_u32 v81, v76, v81, s1
	s_movk_i32 s15, 0x1000
	global_store_short_d16_hi v[86:87], v81, off
	v_bfe_u32 v81, v77, 16, 1
	v_add_co_u32_e32 v88, vcc, s15, v86
	v_add3_u32 v81, v77, v81, s1
	s_nop 0
	v_addc_co_u32_e32 v89, vcc, 0, v87, vcc
	s_movk_i32 s15, 0x2000
	global_store_short_d16_hi v[88:89], v81, off
	v_bfe_u32 v81, v78, 16, 1
	v_add_co_u32_e32 v88, vcc, s15, v86
	v_add3_u32 v81, v78, v81, s1
	s_nop 0
	v_addc_co_u32_e32 v89, vcc, 0, v87, vcc
	s_movk_i32 s15, 0x3000
	global_store_short_d16_hi v[88:89], v81, off
	v_bfe_u32 v81, v79, 16, 1
	v_add_co_u32_e32 v88, vcc, s15, v86
	v_add3_u32 v81, v79, v81, s1
	s_nop 0
	v_addc_co_u32_e32 v89, vcc, 0, v87, vcc
	s_movk_i32 s15, 0x4000
	global_store_short_d16_hi v[88:89], v81, off
	v_bfe_u32 v81, v72, 16, 1
	v_add_co_u32_e32 v88, vcc, s15, v86
	v_add3_u32 v81, v72, v81, s1
	s_nop 0
	v_addc_co_u32_e32 v89, vcc, 0, v87, vcc
	global_store_short_d16_hi v[88:89], v81, off
	v_bfe_u32 v81, v73, 16, 1
	v_add_co_u32_e32 v88, vcc, 0x5000, v86
	v_add3_u32 v81, v73, v81, s1
	s_nop 0
	v_addc_co_u32_e32 v89, vcc, 0, v87, vcc
	global_store_short_d16_hi v[88:89], v81, off
	v_bfe_u32 v81, v74, 16, 1
	v_add_co_u32_e32 v88, vcc, 0x6000, v86
	v_add3_u32 v81, v74, v81, s1
	s_nop 0
	v_addc_co_u32_e32 v89, vcc, 0, v87, vcc
	global_store_short_d16_hi v[88:89], v81, off
	v_bfe_u32 v81, v75, 16, 1
	v_add_co_u32_e32 v86, vcc, 0x7000, v86
	v_add3_u32 v81, v75, v81, s1
	s_nop 0
	v_addc_co_u32_e32 v87, vcc, 0, v87, vcc
	s_mov_b64 s[44:45], 0
	global_store_short_d16_hi v[86:87], v81, off
; __device__ __forceinline__ float rstd4(const float* pp, int row, float invn) { const f32x4 a = *(const f32x4*)(pp + (size_t)row * 4); return rsqrtf(((a.x + a.y) + (a.z + a.w)) * invn + 1e-6f); }
.LBB0_1123:
	v_mad_i64_i32 v[82:83], vcc, v82, s93, 0
	s_andn2_b64 vcc, exec, s[44:45]
	v_lshl_add_u64 v[82:83], s[16:17], 0, v[82:83]
	s_cbranch_vccnz .LBB0_1125
	s_ashr_i32 s31, s30, 31
	v_cvt_pk_bf16_f32 v76, v76, v77
	v_cvt_pk_bf16_f32 v77, v78, v79
	v_cvt_pk_bf16_f32 v78, v72, v73
	v_lshl_add_u64 v[72:73], s[30:31], 1, v[82:83]
	v_cvt_pk_bf16_f32 v79, v74, v75
	v_lshl_add_u64 v[72:73], v[72:73], 0, v[144:145]
	global_store_dwordx4 v[72:73], v[76:79], off
	s_nop 1
.LBB0_1125:
	v_mov_b32_e32 v81, v80
	v_mov_b32_e32 v72, v80
	v_mov_b32_e32 v73, v80
	v_pk_mul_f32 v[70:71], v[70:71], v[72:73]
	v_pk_mul_f32 v[68:69], v[68:69], v[80:81]
	v_pk_mul_f32 v[66:67], v[66:67], v[72:73]
	v_pk_mul_f32 v[64:65], v[64:65], v[80:81]
	s_and_b64 vcc, exec, s[4:5]
	s_mov_b64 s[44:45], -1
	s_cbranch_vccnz .LBB0_1127
	s_add_i32 s14, s14, s51
	s_ashr_i32 s15, s14, 31
	s_lshl_b64 s[14:15], s[14:15], 18
	v_lshl_add_u64 v[72:73], v[138:139], 0, s[14:15]
	v_mov_b32_e32 v85, v145
	v_bfe_u32 v74, v68, 16, 1
	v_lshl_add_u64 v[72:73], v[72:73], 0, v[84:85]
	v_add3_u32 v74, v68, v74, s1
	global_store_short_d16_hi v[72:73], v74, off
	v_bfe_u32 v74, v69, 16, 1
	s_movk_i32 s14, 0x1000
	v_add3_u32 v76, v69, v74, s1
	v_add_co_u32_e32 v74, vcc, s14, v72
	s_movk_i32 s14, 0x2000
	s_nop 0
	v_addc_co_u32_e32 v75, vcc, 0, v73, vcc
	global_store_short_d16_hi v[74:75], v76, off
	v_bfe_u32 v74, v70, 16, 1
	v_add3_u32 v76, v70, v74, s1
	v_add_co_u32_e32 v74, vcc, s14, v72
	s_movk_i32 s14, 0x3000
	s_nop 0
	v_addc_co_u32_e32 v75, vcc, 0, v73, vcc
	global_store_short_d16_hi v[74:75], v76, off
	v_bfe_u32 v74, v71, 16, 1
	v_add3_u32 v76, v71, v74, s1
	v_add_co_u32_e32 v74, vcc, s14, v72
	s_movk_i32 s14, 0x4000
	s_nop 0
	v_addc_co_u32_e32 v75, vcc, 0, v73, vcc
	global_store_short_d16_hi v[74:75], v76, off
	v_bfe_u32 v74, v64, 16, 1
	v_add3_u32 v76, v64, v74, s1
	v_add_co_u32_e32 v74, vcc, s14, v72
	s_mov_b64 s[44:45], 0
	s_nop 0
	v_addc_co_u32_e32 v75, vcc, 0, v73, vcc
	global_store_short_d16_hi v[74:75], v76, off
	v_bfe_u32 v74, v65, 16, 1
	v_add3_u32 v76, v65, v74, s1
	v_add_co_u32_e32 v74, vcc, 0x5000, v72
	s_nop 1
	v_addc_co_u32_e32 v75, vcc, 0, v73, vcc
	global_store_short_d16_hi v[74:75], v76, off
	v_bfe_u32 v74, v66, 16, 1
	v_add3_u32 v76, v66, v74, s1
	v_add_co_u32_e32 v74, vcc, 0x6000, v72
	s_nop 1
	v_addc_co_u32_e32 v75, vcc, 0, v73, vcc
	global_store_short_d16_hi v[74:75], v76, off
	v_bfe_u32 v74, v67, 16, 1
	v_add_co_u32_e32 v72, vcc, 0x7000, v72
	v_add3_u32 v74, v67, v74, s1
	s_nop 0
	v_addc_co_u32_e32 v73, vcc, 0, v73, vcc
	global_store_short_d16_hi v[72:73], v74, off
.LBB0_1127:
	s_andn2_b64 vcc, exec, s[44:45]
	s_cbranch_vccnz .LBB0_1129
	s_ashr_i32 s35, s34, 31
	v_cvt_pk_bf16_f32 v68, v68, v69
	v_cvt_pk_bf16_f32 v69, v70, v71
	v_cvt_pk_bf16_f32 v70, v64, v65
	v_lshl_add_u64 v[64:65], s[34:35], 1, v[82:83]
	v_cvt_pk_bf16_f32 v71, v66, v67
	v_lshl_add_u64 v[64:65], v[64:65], 0, v[144:145]
	global_store_dwordx4 v[64:65], v[68:71], off
	s_nop 1
.LBB0_1129:
	s_addk_i32 s33, 0x80
	s_ashr_i32 s14, s33, 8
	v_or_b32_e32 v64, s33, v137
	s_and_b32 s14, s14, -8
	v_readlane_b32 s44, v254, 12
	v_ashrrev_i32_e32 v65, 31, v64
	v_readlane_b32 s45, v254, 13
	s_mov_b32 s15, 0x800000
	s_nop 0
	v_lshl_add_u64 v[66:67], v[64:65], 4, s[44:45]
	s_mov_b64 s[44:45], -1
	v_mov_b32_e32 v66, v202
	v_mov_b32_e32 v67, v203
	v_mov_b32_e32 v68, v204
	v_mov_b32_e32 v69, v205
	v_mov_b32_e32 v70, v67
	v_mov_b32_e32 v71, v68
	v_mov_b32_e32 v67, v69
	v_pk_add_f32 v[66:67], v[70:71], v[66:67]
	s_nop 0
	v_add_f32_e32 v65, v66, v67
	v_fmamk_f32 v65, v65, 0x3c000000, v171
	v_cmp_gt_f32_e32 vcc, s15, v65
	v_mul_f32_e32 v66, 0x4b800000, v65
	s_nop 0
	v_cndmask_b32_e32 v65, v65, v66, vcc
	v_rsq_f32_e32 v65, v65
	s_nop 0
	v_mul_f32_e32 v66, 0x45800000, v65
	v_cndmask_b32_e32 v66, v65, v66, vcc
	v_bitop3_b32 v65, s33, v178, v137 bitop3:0xc8
	v_pk_mul_f32 v[62:63], v[62:63], v[66:67] op_sel_hi:[1,0]
	v_pk_mul_f32 v[60:61], v[60:61], v[66:67] op_sel_hi:[1,0]
	v_pk_mul_f32 v[58:59], v[58:59], v[66:67] op_sel_hi:[1,0]
	v_pk_mul_f32 v[56:57], v[56:57], v[66:67] op_sel_hi:[1,0]
	s_and_b64 vcc, exec, s[4:5]
	v_lshlrev_b32_e32 v68, 1, v65
	s_cbranch_vccnz .LBB0_1131
	s_add_i32 s44, s14, s50
	s_ashr_i32 s45, s44, 31
	s_lshl_b64 s[44:45], s[44:45], 18
	v_lshl_add_u64 v[70:71], v[138:139], 0, s[44:45]
	v_mov_b32_e32 v69, v145
	v_bfe_u32 v65, v60, 16, 1
	v_lshl_add_u64 v[70:71], v[70:71], 0, v[68:69]
	v_add3_u32 v65, v60, v65, s1
	s_movk_i32 s15, 0x1000
	global_store_short_d16_hi v[70:71], v65, off
	v_bfe_u32 v65, v61, 16, 1
	v_add_co_u32_e32 v72, vcc, s15, v70
	v_add3_u32 v65, v61, v65, s1
	s_nop 0
	v_addc_co_u32_e32 v73, vcc, 0, v71, vcc
	s_movk_i32 s15, 0x2000
	global_store_short_d16_hi v[72:73], v65, off
	v_bfe_u32 v65, v62, 16, 1
	v_add_co_u32_e32 v72, vcc, s15, v70
	v_add3_u32 v65, v62, v65, s1
	s_nop 0
	v_addc_co_u32_e32 v73, vcc, 0, v71, vcc
	s_movk_i32 s15, 0x3000
	global_store_short_d16_hi v[72:73], v65, off
	v_bfe_u32 v65, v63, 16, 1
	v_add_co_u32_e32 v72, vcc, s15, v70
	v_add3_u32 v65, v63, v65, s1
	s_nop 0
	v_addc_co_u32_e32 v73, vcc, 0, v71, vcc
	s_movk_i32 s15, 0x4000
	global_store_short_d16_hi v[72:73], v65, off
	v_bfe_u32 v65, v56, 16, 1
	v_add_co_u32_e32 v72, vcc, s15, v70
	v_add3_u32 v65, v56, v65, s1
	s_nop 0
	v_addc_co_u32_e32 v73, vcc, 0, v71, vcc
	global_store_short_d16_hi v[72:73], v65, off
	v_bfe_u32 v65, v57, 16, 1
	v_add_co_u32_e32 v72, vcc, 0x5000, v70
	v_add3_u32 v65, v57, v65, s1
	s_nop 0
	v_addc_co_u32_e32 v73, vcc, 0, v71, vcc
	global_store_short_d16_hi v[72:73], v65, off
	v_bfe_u32 v65, v58, 16, 1
	v_add_co_u32_e32 v72, vcc, 0x6000, v70
	v_add3_u32 v65, v58, v65, s1
	s_nop 0
	v_addc_co_u32_e32 v73, vcc, 0, v71, vcc
	global_store_short_d16_hi v[72:73], v65, off
	v_bfe_u32 v65, v59, 16, 1
	v_add_co_u32_e32 v70, vcc, 0x7000, v70
	v_add3_u32 v65, v59, v65, s1
	s_nop 0
	v_addc_co_u32_e32 v71, vcc, 0, v71, vcc
	s_mov_b64 s[44:45], 0
	global_store_short_d16_hi v[70:71], v65, off
; __device__ __forceinline__ float rstd4(const float* pp, int row, float invn) { const f32x4 a = *(const f32x4*)(pp + (size_t)row * 4); return rsqrtf(((a.x + a.y) + (a.z + a.w)) * invn + 1e-6f); }
.LBB0_1131:
	v_mad_i64_i32 v[70:71], vcc, v64, s93, 0
	s_andn2_b64 vcc, exec, s[44:45]
	v_lshl_add_u64 v[70:71], s[16:17], 0, v[70:71]
	s_movk_i32 s33, 0x300
	s_cbranch_vccnz .LBB0_1133
	s_ashr_i32 s31, s30, 31
	v_cvt_pk_bf16_f32 v60, v60, v61
	v_cvt_pk_bf16_f32 v61, v62, v63
	v_cvt_pk_bf16_f32 v62, v56, v57
	v_lshl_add_u64 v[56:57], s[30:31], 1, v[70:71]
	v_cvt_pk_bf16_f32 v63, v58, v59
	v_lshl_add_u64 v[56:57], v[56:57], 0, v[144:145]
	global_store_dwordx4 v[56:57], v[60:63], off
	s_nop 1
.LBB0_1133:
	v_mov_b32_e32 v67, v66
	v_mov_b32_e32 v56, v66
	v_mov_b32_e32 v57, v66
	v_pk_mul_f32 v[54:55], v[54:55], v[56:57]
	v_pk_mul_f32 v[52:53], v[52:53], v[66:67]
	v_pk_mul_f32 v[50:51], v[50:51], v[56:57]
	v_pk_mul_f32 v[48:49], v[48:49], v[66:67]
	s_and_b64 vcc, exec, s[4:5]
	s_mov_b64 s[44:45], -1
	s_cbranch_vccnz .LBB0_1135
	s_add_i32 s44, s14, s51
	s_ashr_i32 s45, s44, 31
	s_lshl_b64 s[44:45], s[44:45], 18
	v_lshl_add_u64 v[56:57], v[138:139], 0, s[44:45]
	v_mov_b32_e32 v69, v145
	v_bfe_u32 v58, v52, 16, 1
	v_lshl_add_u64 v[56:57], v[56:57], 0, v[68:69]
	v_add3_u32 v58, v52, v58, s1
	global_store_short_d16_hi v[56:57], v58, off
	v_bfe_u32 v58, v53, 16, 1
	s_movk_i32 s15, 0x1000
	v_add3_u32 v60, v53, v58, s1
	v_add_co_u32_e32 v58, vcc, s15, v56
	s_movk_i32 s15, 0x2000
	s_nop 0
	v_addc_co_u32_e32 v59, vcc, 0, v57, vcc
	global_store_short_d16_hi v[58:59], v60, off
	v_bfe_u32 v58, v54, 16, 1
	v_add3_u32 v60, v54, v58, s1
	v_add_co_u32_e32 v58, vcc, s15, v56
	s_movk_i32 s15, 0x3000
	s_nop 0
	v_addc_co_u32_e32 v59, vcc, 0, v57, vcc
	global_store_short_d16_hi v[58:59], v60, off
	v_bfe_u32 v58, v55, 16, 1
	v_add3_u32 v60, v55, v58, s1
	v_add_co_u32_e32 v58, vcc, s15, v56
	s_movk_i32 s15, 0x4000
	s_nop 0
	v_addc_co_u32_e32 v59, vcc, 0, v57, vcc
	global_store_short_d16_hi v[58:59], v60, off
	v_bfe_u32 v58, v48, 16, 1
	v_add3_u32 v60, v48, v58, s1
	v_add_co_u32_e32 v58, vcc, s15, v56
	s_mov_b64 s[44:45], 0
	s_nop 0
	v_addc_co_u32_e32 v59, vcc, 0, v57, vcc
	global_store_short_d16_hi v[58:59], v60, off
	v_bfe_u32 v58, v49, 16, 1
	v_add3_u32 v60, v49, v58, s1
	v_add_co_u32_e32 v58, vcc, 0x5000, v56
	s_nop 1
	v_addc_co_u32_e32 v59, vcc, 0, v57, vcc
	global_store_short_d16_hi v[58:59], v60, off
	v_bfe_u32 v58, v50, 16, 1
	v_add3_u32 v60, v50, v58, s1
	v_add_co_u32_e32 v58, vcc, 0x6000, v56
	s_nop 1
	v_addc_co_u32_e32 v59, vcc, 0, v57, vcc
	global_store_short_d16_hi v[58:59], v60, off
	v_bfe_u32 v58, v51, 16, 1
	v_add_co_u32_e32 v56, vcc, 0x7000, v56
	v_add3_u32 v58, v51, v58, s1
	s_nop 0
	v_addc_co_u32_e32 v57, vcc, 0, v57, vcc
	global_store_short_d16_hi v[56:57], v58, off
.LBB0_1135:
	s_andn2_b64 vcc, exec, s[44:45]
	s_cbranch_vccnz .LBB0_1137
	s_ashr_i32 s35, s34, 31
	v_cvt_pk_bf16_f32 v52, v52, v53
	v_cvt_pk_bf16_f32 v53, v54, v55
	v_cvt_pk_bf16_f32 v54, v48, v49
	v_lshl_add_u64 v[48:49], s[34:35], 1, v[70:71]
	v_cvt_pk_bf16_f32 v55, v50, v51
	v_lshl_add_u64 v[48:49], v[48:49], 0, v[144:145]
	global_store_dwordx4 v[48:49], v[52:55], off
	s_nop 1
.LBB0_1137:
	v_or_b32_e32 v50, 16, v64
	v_readlane_b32 s44, v254, 12
	v_ashrrev_i32_e32 v51, 31, v50
	v_readlane_b32 s45, v254, 13
	s_mov_b32 s15, 0x800000
	s_nop 0
	v_lshl_add_u64 v[48:49], v[50:51], 4, s[44:45]
	s_mov_b64 s[44:45], -1
	v_mov_b32_e32 v52, v206
	v_mov_b32_e32 v53, v207
	v_mov_b32_e32 v54, v208
	v_mov_b32_e32 v55, v209
	v_mov_b32_e32 v48, v53
	v_mov_b32_e32 v49, v54
	v_mov_b32_e32 v53, v55
	v_pk_add_f32 v[48:49], v[48:49], v[52:53]
	s_nop 0
	v_add_f32_e32 v48, v48, v49
	v_fmamk_f32 v48, v48, 0x3c000000, v171
	v_cmp_gt_f32_e32 vcc, s15, v48
	v_mul_f32_e32 v49, 0x4b800000, v48
	s_movk_i32 s15, 0x7df
	v_cndmask_b32_e32 v48, v48, v49, vcc
	v_rsq_f32_e32 v48, v48
	s_nop 0
	v_mul_f32_e32 v49, 0x45800000, v48
	v_cndmask_b32_e32 v48, v48, v49, vcc
	v_bitop3_b32 v49, v64, s15, 16 bitop3:0xc8
	v_pk_mul_f32 v[46:47], v[46:47], v[48:49] op_sel_hi:[1,0]
	v_pk_mul_f32 v[44:45], v[44:45], v[48:49] op_sel_hi:[1,0]
	v_pk_mul_f32 v[42:43], v[42:43], v[48:49] op_sel_hi:[1,0]
	v_pk_mul_f32 v[40:41], v[40:41], v[48:49] op_sel_hi:[1,0]
	s_and_b64 vcc, exec, s[4:5]
	v_lshlrev_b32_e32 v52, 1, v49
	s_cbranch_vccnz .LBB0_1139
	s_add_i32 s44, s14, s50
	s_ashr_i32 s45, s44, 31
	s_lshl_b64 s[44:45], s[44:45], 18
	v_lshl_add_u64 v[54:55], v[138:139], 0, s[44:45]
	v_mov_b32_e32 v53, v145
	v_bfe_u32 v49, v44, 16, 1
	v_lshl_add_u64 v[54:55], v[54:55], 0, v[52:53]
	v_add3_u32 v49, v44, v49, s1
	s_movk_i32 s15, 0x1000
	global_store_short_d16_hi v[54:55], v49, off
	v_bfe_u32 v49, v45, 16, 1
	v_add_co_u32_e32 v56, vcc, s15, v54
	v_add3_u32 v49, v45, v49, s1
	s_nop 0
	v_addc_co_u32_e32 v57, vcc, 0, v55, vcc
	s_movk_i32 s15, 0x2000
	global_store_short_d16_hi v[56:57], v49, off
	v_bfe_u32 v49, v46, 16, 1
	v_add_co_u32_e32 v56, vcc, s15, v54
	v_add3_u32 v49, v46, v49, s1
	s_nop 0
	v_addc_co_u32_e32 v57, vcc, 0, v55, vcc
	s_movk_i32 s15, 0x3000
	global_store_short_d16_hi v[56:57], v49, off
	v_bfe_u32 v49, v47, 16, 1
	v_add_co_u32_e32 v56, vcc, s15, v54
	v_add3_u32 v49, v47, v49, s1
	s_nop 0
	v_addc_co_u32_e32 v57, vcc, 0, v55, vcc
	s_movk_i32 s15, 0x4000
	global_store_short_d16_hi v[56:57], v49, off
	v_bfe_u32 v49, v40, 16, 1
	v_add_co_u32_e32 v56, vcc, s15, v54
	v_add3_u32 v49, v40, v49, s1
	s_nop 0
	v_addc_co_u32_e32 v57, vcc, 0, v55, vcc
	global_store_short_d16_hi v[56:57], v49, off
	v_bfe_u32 v49, v41, 16, 1
	v_add_co_u32_e32 v56, vcc, 0x5000, v54
	v_add3_u32 v49, v41, v49, s1
	s_nop 0
	v_addc_co_u32_e32 v57, vcc, 0, v55, vcc
	global_store_short_d16_hi v[56:57], v49, off
	v_bfe_u32 v49, v42, 16, 1
	v_add_co_u32_e32 v56, vcc, 0x6000, v54
	v_add3_u32 v49, v42, v49, s1
	s_nop 0
	v_addc_co_u32_e32 v57, vcc, 0, v55, vcc
	global_store_short_d16_hi v[56:57], v49, off
	v_bfe_u32 v49, v43, 16, 1
	v_add_co_u32_e32 v54, vcc, 0x7000, v54
	v_add3_u32 v49, v43, v49, s1
	s_nop 0
	v_addc_co_u32_e32 v55, vcc, 0, v55, vcc
	s_mov_b64 s[44:45], 0
	global_store_short_d16_hi v[54:55], v49, off
; __device__ __forceinline__ float rstd4(const float* pp, int row, float invn) { const f32x4 a = *(const f32x4*)(pp + (size_t)row * 4); return rsqrtf(((a.x + a.y) + (a.z + a.w)) * invn + 1e-6f); }
.LBB0_1139:
	v_mad_i64_i32 v[50:51], vcc, v50, s93, 0
	s_andn2_b64 vcc, exec, s[44:45]
	v_lshl_add_u64 v[50:51], s[16:17], 0, v[50:51]
	s_cbranch_vccnz .LBB0_1141
	s_ashr_i32 s31, s30, 31
	v_cvt_pk_bf16_f32 v44, v44, v45
	v_cvt_pk_bf16_f32 v45, v46, v47
	v_cvt_pk_bf16_f32 v46, v40, v41
	v_lshl_add_u64 v[40:41], s[30:31], 1, v[50:51]
	v_cvt_pk_bf16_f32 v47, v42, v43
	v_lshl_add_u64 v[40:41], v[40:41], 0, v[144:145]
	global_store_dwordx4 v[40:41], v[44:47], off
	s_nop 1
.LBB0_1141:
	v_mov_b32_e32 v49, v48
	v_mov_b32_e32 v40, v48
	v_mov_b32_e32 v41, v48
	v_pk_mul_f32 v[38:39], v[38:39], v[40:41]
	v_pk_mul_f32 v[36:37], v[36:37], v[48:49]
	v_pk_mul_f32 v[34:35], v[34:35], v[40:41]
	v_pk_mul_f32 v[32:33], v[32:33], v[48:49]
	s_and_b64 vcc, exec, s[4:5]
	s_mov_b64 s[44:45], -1
	s_cbranch_vccnz .LBB0_1143
	s_add_i32 s44, s14, s51
	s_ashr_i32 s45, s44, 31
	s_lshl_b64 s[44:45], s[44:45], 18
	v_lshl_add_u64 v[40:41], v[138:139], 0, s[44:45]
	v_mov_b32_e32 v53, v145
	v_bfe_u32 v42, v36, 16, 1
	v_lshl_add_u64 v[40:41], v[40:41], 0, v[52:53]
	v_add3_u32 v42, v36, v42, s1
	global_store_short_d16_hi v[40:41], v42, off
	v_bfe_u32 v42, v37, 16, 1
	s_movk_i32 s15, 0x1000
	v_add3_u32 v44, v37, v42, s1
	v_add_co_u32_e32 v42, vcc, s15, v40
	s_movk_i32 s15, 0x2000
	s_nop 0
	v_addc_co_u32_e32 v43, vcc, 0, v41, vcc
	global_store_short_d16_hi v[42:43], v44, off
	v_bfe_u32 v42, v38, 16, 1
	v_add3_u32 v44, v38, v42, s1
	v_add_co_u32_e32 v42, vcc, s15, v40
	s_movk_i32 s15, 0x3000
	s_nop 0
	v_addc_co_u32_e32 v43, vcc, 0, v41, vcc
	global_store_short_d16_hi v[42:43], v44, off
	v_bfe_u32 v42, v39, 16, 1
	v_add3_u32 v44, v39, v42, s1
	v_add_co_u32_e32 v42, vcc, s15, v40
	s_movk_i32 s15, 0x4000
	s_nop 0
	v_addc_co_u32_e32 v43, vcc, 0, v41, vcc
	global_store_short_d16_hi v[42:43], v44, off
	v_bfe_u32 v42, v32, 16, 1
	v_add3_u32 v44, v32, v42, s1
	v_add_co_u32_e32 v42, vcc, s15, v40
	s_mov_b64 s[44:45], 0
	s_nop 0
	v_addc_co_u32_e32 v43, vcc, 0, v41, vcc
	global_store_short_d16_hi v[42:43], v44, off
	v_bfe_u32 v42, v33, 16, 1
	v_add3_u32 v44, v33, v42, s1
	v_add_co_u32_e32 v42, vcc, 0x5000, v40
	s_nop 1
	v_addc_co_u32_e32 v43, vcc, 0, v41, vcc
	global_store_short_d16_hi v[42:43], v44, off
	v_bfe_u32 v42, v34, 16, 1
	v_add3_u32 v44, v34, v42, s1
	v_add_co_u32_e32 v42, vcc, 0x6000, v40
	s_nop 1
	v_addc_co_u32_e32 v43, vcc, 0, v41, vcc
	global_store_short_d16_hi v[42:43], v44, off
	v_bfe_u32 v42, v35, 16, 1
	v_add_co_u32_e32 v40, vcc, 0x7000, v40
	v_add3_u32 v42, v35, v42, s1
	s_nop 0
	v_addc_co_u32_e32 v41, vcc, 0, v41, vcc
	global_store_short_d16_hi v[40:41], v42, off
.LBB0_1143:
	s_andn2_b64 vcc, exec, s[44:45]
	s_cbranch_vccnz .LBB0_1145
	s_ashr_i32 s35, s34, 31
	v_cvt_pk_bf16_f32 v36, v36, v37
	v_cvt_pk_bf16_f32 v37, v38, v39
	v_cvt_pk_bf16_f32 v38, v32, v33
	v_lshl_add_u64 v[32:33], s[34:35], 1, v[50:51]
	v_cvt_pk_bf16_f32 v39, v34, v35
	v_lshl_add_u64 v[32:33], v[32:33], 0, v[144:145]
	global_store_dwordx4 v[32:33], v[36:39], off
	s_nop 1
.LBB0_1145:
	v_or_b32_e32 v34, 32, v64
	v_readlane_b32 s44, v254, 12
	v_ashrrev_i32_e32 v35, 31, v34
	v_readlane_b32 s45, v254, 13
	s_mov_b32 s15, 0x800000
	s_nop 0
	v_lshl_add_u64 v[32:33], v[34:35], 4, s[44:45]
	s_mov_b64 s[44:45], -1
	v_mov_b32_e32 v36, v210
	v_mov_b32_e32 v37, v211
	v_mov_b32_e32 v38, v212
	v_mov_b32_e32 v39, v213
	v_mov_b32_e32 v32, v37
	v_mov_b32_e32 v33, v38
	v_mov_b32_e32 v37, v39
	v_pk_add_f32 v[32:33], v[32:33], v[36:37]
	s_nop 0
	v_add_f32_e32 v32, v32, v33
	v_fmamk_f32 v32, v32, 0x3c000000, v171
	v_cmp_gt_f32_e32 vcc, s15, v32
	v_mul_f32_e32 v33, 0x4b800000, v32
	s_movk_i32 s15, 0x7ef
	v_cndmask_b32_e32 v32, v32, v33, vcc
	v_rsq_f32_e32 v32, v32
	s_nop 0
	v_mul_f32_e32 v33, 0x45800000, v32
	v_cndmask_b32_e32 v32, v32, v33, vcc
	v_bitop3_b32 v33, v64, s15, 32 bitop3:0xc8
	v_pk_mul_f32 v[30:31], v[30:31], v[32:33] op_sel_hi:[1,0]
	v_pk_mul_f32 v[28:29], v[28:29], v[32:33] op_sel_hi:[1,0]
	v_pk_mul_f32 v[26:27], v[26:27], v[32:33] op_sel_hi:[1,0]
	v_pk_mul_f32 v[24:25], v[24:25], v[32:33] op_sel_hi:[1,0]
	s_and_b64 vcc, exec, s[4:5]
	v_lshlrev_b32_e32 v36, 1, v33
	s_cbranch_vccnz .LBB0_1147
	s_add_i32 s44, s14, s50
	s_ashr_i32 s45, s44, 31
	s_lshl_b64 s[44:45], s[44:45], 18
	v_lshl_add_u64 v[38:39], v[138:139], 0, s[44:45]
	v_mov_b32_e32 v37, v145
	v_bfe_u32 v33, v28, 16, 1
	v_lshl_add_u64 v[38:39], v[38:39], 0, v[36:37]
	v_add3_u32 v33, v28, v33, s1
	s_movk_i32 s15, 0x1000
	global_store_short_d16_hi v[38:39], v33, off
	v_bfe_u32 v33, v29, 16, 1
	v_add_co_u32_e32 v40, vcc, s15, v38
	v_add3_u32 v33, v29, v33, s1
	s_nop 0
	v_addc_co_u32_e32 v41, vcc, 0, v39, vcc
	s_movk_i32 s15, 0x2000
	global_store_short_d16_hi v[40:41], v33, off
	v_bfe_u32 v33, v30, 16, 1
	v_add_co_u32_e32 v40, vcc, s15, v38
	v_add3_u32 v33, v30, v33, s1
	s_nop 0
	v_addc_co_u32_e32 v41, vcc, 0, v39, vcc
	s_movk_i32 s15, 0x3000
	global_store_short_d16_hi v[40:41], v33, off
	v_bfe_u32 v33, v31, 16, 1
	v_add_co_u32_e32 v40, vcc, s15, v38
	v_add3_u32 v33, v31, v33, s1
	s_nop 0
	v_addc_co_u32_e32 v41, vcc, 0, v39, vcc
	s_movk_i32 s15, 0x4000
	global_store_short_d16_hi v[40:41], v33, off
	v_bfe_u32 v33, v24, 16, 1
	v_add_co_u32_e32 v40, vcc, s15, v38
	v_add3_u32 v33, v24, v33, s1
	s_nop 0
	v_addc_co_u32_e32 v41, vcc, 0, v39, vcc
	global_store_short_d16_hi v[40:41], v33, off
	v_bfe_u32 v33, v25, 16, 1
	v_add_co_u32_e32 v40, vcc, 0x5000, v38
	v_add3_u32 v33, v25, v33, s1
	s_nop 0
	v_addc_co_u32_e32 v41, vcc, 0, v39, vcc
	global_store_short_d16_hi v[40:41], v33, off
	v_bfe_u32 v33, v26, 16, 1
	v_add_co_u32_e32 v40, vcc, 0x6000, v38
	v_add3_u32 v33, v26, v33, s1
	s_nop 0
	v_addc_co_u32_e32 v41, vcc, 0, v39, vcc
	global_store_short_d16_hi v[40:41], v33, off
	v_bfe_u32 v33, v27, 16, 1
	v_add_co_u32_e32 v38, vcc, 0x7000, v38
	v_add3_u32 v33, v27, v33, s1
	s_nop 0
	v_addc_co_u32_e32 v39, vcc, 0, v39, vcc
	s_mov_b64 s[44:45], 0
	global_store_short_d16_hi v[38:39], v33, off
; __device__ __forceinline__ float rstd4(const float* pp, int row, float invn) { const f32x4 a = *(const f32x4*)(pp + (size_t)row * 4); return rsqrtf(((a.x + a.y) + (a.z + a.w)) * invn + 1e-6f); }
.LBB0_1147:
	v_mad_i64_i32 v[34:35], vcc, v34, s93, 0
	s_andn2_b64 vcc, exec, s[44:45]
	v_lshl_add_u64 v[34:35], s[16:17], 0, v[34:35]
	s_cbranch_vccnz .LBB0_1149
	s_ashr_i32 s31, s30, 31
	v_cvt_pk_bf16_f32 v28, v28, v29
	v_cvt_pk_bf16_f32 v29, v30, v31
	v_cvt_pk_bf16_f32 v30, v24, v25
	v_lshl_add_u64 v[24:25], s[30:31], 1, v[34:35]
	v_cvt_pk_bf16_f32 v31, v26, v27
	v_lshl_add_u64 v[24:25], v[24:25], 0, v[144:145]
	global_store_dwordx4 v[24:25], v[28:31], off
	s_nop 1
.LBB0_1149:
	v_mov_b32_e32 v33, v32
	v_mov_b32_e32 v24, v32
	v_mov_b32_e32 v25, v32
	v_pk_mul_f32 v[22:23], v[22:23], v[24:25]
	v_pk_mul_f32 v[20:21], v[20:21], v[32:33]
	v_pk_mul_f32 v[18:19], v[18:19], v[24:25]
	v_pk_mul_f32 v[16:17], v[16:17], v[32:33]
	s_and_b64 vcc, exec, s[4:5]
	s_mov_b64 s[44:45], -1
	s_cbranch_vccnz .LBB0_1151
	s_add_i32 s44, s14, s51
	s_ashr_i32 s45, s44, 31
	s_lshl_b64 s[44:45], s[44:45], 18
	v_lshl_add_u64 v[24:25], v[138:139], 0, s[44:45]
	v_mov_b32_e32 v37, v145
	v_bfe_u32 v26, v20, 16, 1
	v_lshl_add_u64 v[24:25], v[24:25], 0, v[36:37]
	v_add3_u32 v26, v20, v26, s1
	global_store_short_d16_hi v[24:25], v26, off
	v_bfe_u32 v26, v21, 16, 1
	s_movk_i32 s15, 0x1000
	v_add3_u32 v28, v21, v26, s1
	v_add_co_u32_e32 v26, vcc, s15, v24
	s_movk_i32 s15, 0x2000
	s_nop 0
	v_addc_co_u32_e32 v27, vcc, 0, v25, vcc
	global_store_short_d16_hi v[26:27], v28, off
	v_bfe_u32 v26, v22, 16, 1
	v_add3_u32 v28, v22, v26, s1
	v_add_co_u32_e32 v26, vcc, s15, v24
	s_movk_i32 s15, 0x3000
	s_nop 0
	v_addc_co_u32_e32 v27, vcc, 0, v25, vcc
	global_store_short_d16_hi v[26:27], v28, off
	v_bfe_u32 v26, v23, 16, 1
	v_add3_u32 v28, v23, v26, s1
	v_add_co_u32_e32 v26, vcc, s15, v24
	s_movk_i32 s15, 0x4000
	s_nop 0
	v_addc_co_u32_e32 v27, vcc, 0, v25, vcc
	global_store_short_d16_hi v[26:27], v28, off
	v_bfe_u32 v26, v16, 16, 1
	v_add3_u32 v28, v16, v26, s1
	v_add_co_u32_e32 v26, vcc, s15, v24
	s_mov_b64 s[44:45], 0
	s_nop 0
	v_addc_co_u32_e32 v27, vcc, 0, v25, vcc
	global_store_short_d16_hi v[26:27], v28, off
	v_bfe_u32 v26, v17, 16, 1
	v_add3_u32 v28, v17, v26, s1
	v_add_co_u32_e32 v26, vcc, 0x5000, v24
	s_nop 1
	v_addc_co_u32_e32 v27, vcc, 0, v25, vcc
	global_store_short_d16_hi v[26:27], v28, off
	v_bfe_u32 v26, v18, 16, 1
	v_add3_u32 v28, v18, v26, s1
	v_add_co_u32_e32 v26, vcc, 0x6000, v24
	s_nop 1
	v_addc_co_u32_e32 v27, vcc, 0, v25, vcc
	global_store_short_d16_hi v[26:27], v28, off
	v_bfe_u32 v26, v19, 16, 1
	v_add_co_u32_e32 v24, vcc, 0x7000, v24
	v_add3_u32 v26, v19, v26, s1
	s_nop 0
	v_addc_co_u32_e32 v25, vcc, 0, v25, vcc
	global_store_short_d16_hi v[24:25], v26, off
.LBB0_1151:
	s_andn2_b64 vcc, exec, s[44:45]
	s_cbranch_vccnz .LBB0_1153
	s_ashr_i32 s35, s34, 31
	v_cvt_pk_bf16_f32 v20, v20, v21
	v_cvt_pk_bf16_f32 v21, v22, v23
	v_cvt_pk_bf16_f32 v22, v16, v17
	v_lshl_add_u64 v[16:17], s[34:35], 1, v[34:35]
	v_cvt_pk_bf16_f32 v23, v18, v19
	v_lshl_add_u64 v[16:17], v[16:17], 0, v[144:145]
	global_store_dwordx4 v[16:17], v[20:23], off
	s_nop 1
.LBB0_1153:
	v_or_b32_e32 v18, 48, v64
	v_readlane_b32 s44, v254, 12
	v_ashrrev_i32_e32 v19, 31, v18
	v_readlane_b32 s45, v254, 13
	s_mov_b32 s15, 0x800000
	s_nop 0
	v_lshl_add_u64 v[16:17], v[18:19], 4, s[44:45]
	s_mov_b64 s[44:45], -1
	v_mov_b32_e32 v20, v214
	v_mov_b32_e32 v21, v215
	v_mov_b32_e32 v22, v216
	v_mov_b32_e32 v23, v217
	v_mov_b32_e32 v16, v21
	v_mov_b32_e32 v17, v22
	v_mov_b32_e32 v21, v23
	v_pk_add_f32 v[16:17], v[16:17], v[20:21]
	s_nop 0
	v_add_f32_e32 v16, v16, v17
	v_fmamk_f32 v16, v16, 0x3c000000, v171
	v_cmp_gt_f32_e32 vcc, s15, v16
	v_mul_f32_e32 v17, 0x4b800000, v16
	s_movk_i32 s15, 0x7ff
	v_cndmask_b32_e32 v16, v16, v17, vcc
	v_rsq_f32_e32 v16, v16
	s_nop 0
	v_mul_f32_e32 v17, 0x45800000, v16
	v_cndmask_b32_e32 v16, v16, v17, vcc
	v_bitop3_b32 v17, v64, s15, 48 bitop3:0xc8
	v_pk_mul_f32 v[14:15], v[14:15], v[16:17] op_sel_hi:[1,0]
	v_pk_mul_f32 v[12:13], v[12:13], v[16:17] op_sel_hi:[1,0]
	v_pk_mul_f32 v[10:11], v[10:11], v[16:17] op_sel_hi:[1,0]
	v_pk_mul_f32 v[8:9], v[8:9], v[16:17] op_sel_hi:[1,0]
	s_and_b64 vcc, exec, s[4:5]
	v_lshlrev_b32_e32 v20, 1, v17
	s_cbranch_vccnz .LBB0_1155
	s_add_i32 s44, s14, s50
	s_ashr_i32 s45, s44, 31
	s_lshl_b64 s[44:45], s[44:45], 18
	v_lshl_add_u64 v[22:23], v[138:139], 0, s[44:45]
	v_mov_b32_e32 v21, v145
	v_bfe_u32 v17, v12, 16, 1
	v_lshl_add_u64 v[22:23], v[22:23], 0, v[20:21]
	v_add3_u32 v17, v12, v17, s1
	s_movk_i32 s15, 0x1000
	global_store_short_d16_hi v[22:23], v17, off
	v_bfe_u32 v17, v13, 16, 1
	v_add_co_u32_e32 v24, vcc, s15, v22
	v_add3_u32 v17, v13, v17, s1
	s_nop 0
	v_addc_co_u32_e32 v25, vcc, 0, v23, vcc
	s_movk_i32 s15, 0x2000
	global_store_short_d16_hi v[24:25], v17, off
	v_bfe_u32 v17, v14, 16, 1
	v_add_co_u32_e32 v24, vcc, s15, v22
	v_add3_u32 v17, v14, v17, s1
	s_nop 0
	v_addc_co_u32_e32 v25, vcc, 0, v23, vcc
	s_movk_i32 s15, 0x3000
	global_store_short_d16_hi v[24:25], v17, off
	v_bfe_u32 v17, v15, 16, 1
	v_add_co_u32_e32 v24, vcc, s15, v22
	v_add3_u32 v17, v15, v17, s1
	s_nop 0
	v_addc_co_u32_e32 v25, vcc, 0, v23, vcc
	s_movk_i32 s15, 0x4000
	global_store_short_d16_hi v[24:25], v17, off
	v_bfe_u32 v17, v8, 16, 1
	v_add_co_u32_e32 v24, vcc, s15, v22
	v_add3_u32 v17, v8, v17, s1
	s_nop 0
	v_addc_co_u32_e32 v25, vcc, 0, v23, vcc
	global_store_short_d16_hi v[24:25], v17, off
	v_bfe_u32 v17, v9, 16, 1
	v_add_co_u32_e32 v24, vcc, 0x5000, v22
	v_add3_u32 v17, v9, v17, s1
	s_nop 0
	v_addc_co_u32_e32 v25, vcc, 0, v23, vcc
	global_store_short_d16_hi v[24:25], v17, off
	v_bfe_u32 v17, v10, 16, 1
	v_add_co_u32_e32 v24, vcc, 0x6000, v22
	v_add3_u32 v17, v10, v17, s1
	s_nop 0
	v_addc_co_u32_e32 v25, vcc, 0, v23, vcc
	global_store_short_d16_hi v[24:25], v17, off
	v_bfe_u32 v17, v11, 16, 1
	v_add_co_u32_e32 v22, vcc, 0x7000, v22
	v_add3_u32 v17, v11, v17, s1
	s_nop 0
	v_addc_co_u32_e32 v23, vcc, 0, v23, vcc
	s_mov_b64 s[44:45], 0
	global_store_short_d16_hi v[22:23], v17, off
.LBB0_1155:
	v_mad_i64_i32 v[18:19], vcc, v18, s93, 0
	s_andn2_b64 vcc, exec, s[44:45]
	v_lshl_add_u64 v[18:19], s[16:17], 0, v[18:19]
	s_cbranch_vccnz .LBB0_1157
	s_ashr_i32 s31, s30, 31
	v_cvt_pk_bf16_f32 v12, v12, v13
	v_cvt_pk_bf16_f32 v13, v14, v15
	v_cvt_pk_bf16_f32 v14, v8, v9
	v_lshl_add_u64 v[8:9], s[30:31], 1, v[18:19]
	v_cvt_pk_bf16_f32 v15, v10, v11
	v_lshl_add_u64 v[8:9], v[8:9], 0, v[144:145]
	global_store_dwordx4 v[8:9], v[12:15], off
	s_nop 1

.LBB0_1160:
	s_add_i32 s4, s14, s51
	s_ashr_i32 s5, s4, 31
	s_lshl_b64 s[4:5], s[4:5], 18
	v_lshl_add_u64 v[8:9], v[138:139], 0, s[4:5]
	v_mov_b32_e32 v21, v145
	v_bfe_u32 v10, v4, 16, 1
	v_lshl_add_u64 v[8:9], v[8:9], 0, v[20:21]
	v_add3_u32 v10, v4, v10, s1
	global_store_short_d16_hi v[8:9], v10, off
	v_bfe_u32 v10, v5, 16, 1
	s_movk_i32 s4, 0x1000
	v_add3_u32 v12, v5, v10, s1
	v_add_co_u32_e32 v10, vcc, s4, v8
	s_movk_i32 s4, 0x2000
	s_nop 0
	v_addc_co_u32_e32 v11, vcc, 0, v9, vcc
	global_store_short_d16_hi v[10:11], v12, off
	v_bfe_u32 v10, v6, 16, 1
	v_add3_u32 v12, v6, v10, s1
	v_add_co_u32_e32 v10, vcc, s4, v8
	s_movk_i32 s4, 0x3000
	s_nop 0
	v_addc_co_u32_e32 v11, vcc, 0, v9, vcc
	global_store_short_d16_hi v[10:11], v12, off
	v_bfe_u32 v10, v7, 16, 1
	v_add3_u32 v12, v7, v10, s1
	v_add_co_u32_e32 v10, vcc, s4, v8
	s_movk_i32 s4, 0x4000
	s_nop 0
	v_addc_co_u32_e32 v11, vcc, 0, v9, vcc
	global_store_short_d16_hi v[10:11], v12, off
	v_bfe_u32 v10, v0, 16, 1
	v_add3_u32 v12, v0, v10, s1
	v_add_co_u32_e32 v10, vcc, s4, v8
	s_nop 1
	v_addc_co_u32_e32 v11, vcc, 0, v9, vcc
	global_store_short_d16_hi v[10:11], v12, off
	v_bfe_u32 v10, v1, 16, 1
	v_add3_u32 v12, v1, v10, s1
	v_add_co_u32_e32 v10, vcc, 0x5000, v8
	s_nop 1
	v_addc_co_u32_e32 v11, vcc, 0, v9, vcc
	global_store_short_d16_hi v[10:11], v12, off
	v_bfe_u32 v10, v2, 16, 1
	v_add3_u32 v12, v2, v10, s1
	v_add_co_u32_e32 v10, vcc, 0x6000, v8
	s_nop 1
	v_addc_co_u32_e32 v11, vcc, 0, v9, vcc
	global_store_short_d16_hi v[10:11], v12, off
	v_bfe_u32 v10, v3, 16, 1
	v_add_co_u32_e32 v8, vcc, 0x7000, v8
	v_add3_u32 v10, v3, v10, s1
	s_nop 0
	v_addc_co_u32_e32 v9, vcc, 0, v9, vcc
	global_store_short_d16_hi v[8:9], v10, off
	s_cbranch_execnz .LBB0_1159
.LBB0_1161:
	s_ashr_i32 s35, s34, 31
	v_cvt_pk_bf16_f32 v4, v4, v5
	v_cvt_pk_bf16_f32 v5, v6, v7
	v_cvt_pk_bf16_f32 v6, v0, v1
	v_lshl_add_u64 v[0:1], s[34:35], 1, v[18:19]
	v_cvt_pk_bf16_f32 v7, v2, v3
	v_lshl_add_u64 v[0:1], v[0:1], 0, v[144:145]
	global_store_dwordx4 v[0:1], v[4:7], off
	s_nop 1
	s_and_b64 vcc, exec, s[2:3]
	s_mov_b64 s[2:3], -1
	s_movk_i32 s51, 0x200
	s_cbranch_vccnz .LBB0_1080

.LBB0_1606:
	s_lshr_b64 s[2:3], s[34:35], 10
	s_lshl_b32 s52, s2, 10
	s_ashr_i32 s53, s52, 31
	v_lshl_or_b32 v138, s49, 8, v158
	s_cmp_gt_i32 s2, 0
	v_ashrrev_i32_e32 v139, 31, v138
	s_cselect_b64 s[46:47], -1, 0
	s_lshl_b32 s48, s48, 8
	s_cmp_lt_i32 s2, 1
	v_add_u32_e32 v140, s48, v156
	v_mov_b64_e32 v[154:155], s[14:15]
	s_movk_i32 s3, 0xc00
	v_mad_i64_i32 v[154:155], s[34:35], v140, s3, v[154:155]
	v_lshl_add_u64 v[154:155], v[154:155], 0, s[52:53]
	v_lshl_add_u64 v[154:155], v[154:155], 0, v[138:139]
	v_mov_b32_e32 v240, v140
	v_mov_b32_e32 v241, 0
	v_lshlrev_b64 v[240:241], 10, v[240:241]
	v_lshl_add_u64 v[242:243], v[240:241], 1, v[240:241]
	v_lshl_add_u64 v[242:243], v[242:243], 0, s[14:15]
	v_lshl_add_u64 v[242:243], v[242:243], 0, s[52:53]
	v_lshl_add_u64 v[242:243], v[242:243], 0, v[138:139]
	global_load_dwordx2 v[192:193], v[242:243], off
	global_load_dwordx2 v[194:195], v[242:243], off offset:128
	v_add_u32_e32 v240, 16, v140
	v_mov_b32_e32 v241, 0
	v_lshlrev_b64 v[240:241], 10, v[240:241]
	v_lshl_add_u64 v[242:243], v[240:241], 1, v[240:241]
	v_lshl_add_u64 v[242:243], v[242:243], 0, s[14:15]
	v_lshl_add_u64 v[242:243], v[242:243], 0, s[52:53]
	v_lshl_add_u64 v[242:243], v[242:243], 0, v[138:139]
	global_load_dwordx2 v[196:197], v[242:243], off
	global_load_dwordx2 v[198:199], v[242:243], off offset:128
	v_add_u32_e32 v240, 32, v140
	v_mov_b32_e32 v241, 0
	v_lshlrev_b64 v[240:241], 10, v[240:241]
	v_lshl_add_u64 v[242:243], v[240:241], 1, v[240:241]
	v_lshl_add_u64 v[242:243], v[242:243], 0, s[14:15]
	v_lshl_add_u64 v[242:243], v[242:243], 0, s[52:53]
	v_lshl_add_u64 v[242:243], v[242:243], 0, v[138:139]
	global_load_dwordx2 v[200:201], v[242:243], off
	global_load_dwordx2 v[202:203], v[242:243], off offset:128
	v_add_u32_e32 v240, 48, v140
	v_mov_b32_e32 v241, 0
	v_lshlrev_b64 v[240:241], 10, v[240:241]
	v_lshl_add_u64 v[242:243], v[240:241], 1, v[240:241]
	v_lshl_add_u64 v[242:243], v[242:243], 0, s[14:15]
	v_lshl_add_u64 v[242:243], v[242:243], 0, s[52:53]
	v_lshl_add_u64 v[242:243], v[242:243], 0, v[138:139]
	global_load_dwordx2 v[204:205], v[242:243], off
	global_load_dwordx2 v[206:207], v[242:243], off offset:128
	s_cbranch_scc1 .Lmy_pj_skipA
	v_mov_b32_e32 v240, v140
	v_mov_b32_e32 v241, 0
	v_lshlrev_b64 v[240:241], 10, v[240:241]
	v_lshl_add_u64 v[166:167], v[240:241], 0, v[138:139]
	v_lshl_add_u64 v[166:167], v[166:167], 1, s[16:17]
	global_load_dwordx4 v[208:211], v[166:167], off
	global_load_dwordx4 v[212:215], v[166:167], off offset:256
	v_add_u32_e32 v240, 16, v140
	v_mov_b32_e32 v241, 0
	v_lshlrev_b64 v[240:241], 10, v[240:241]
	v_lshl_add_u64 v[166:167], v[240:241], 0, v[138:139]
	v_lshl_add_u64 v[166:167], v[166:167], 1, s[16:17]
	global_load_dwordx4 v[216:219], v[166:167], off
	global_load_dwordx4 v[220:223], v[166:167], off offset:256
	v_add_u32_e32 v240, 32, v140
	v_mov_b32_e32 v241, 0
	v_lshlrev_b64 v[240:241], 10, v[240:241]
	v_lshl_add_u64 v[166:167], v[240:241], 0, v[138:139]
	v_lshl_add_u64 v[166:167], v[166:167], 1, s[16:17]
	global_load_dwordx4 v[224:227], v[166:167], off
	global_load_dwordx4 v[228:231], v[166:167], off offset:256
	v_add_u32_e32 v240, 48, v140
	v_mov_b32_e32 v241, 0
	v_lshlrev_b64 v[240:241], 10, v[240:241]
	v_lshl_add_u64 v[166:167], v[240:241], 0, v[138:139]
	v_lshl_add_u64 v[166:167], v[166:167], 1, s[16:17]
	global_load_dwordx4 v[232:235], v[166:167], off
	global_load_dwordx4 v[236:239], v[166:167], off offset:256
.Lmy_pj_skipA:
	s_waitcnt vmcnt(0)
	s_mov_b32 s34, 0x3b808081
	v_ashrrev_i32_e32 v141, 31, v140
	v_lshlrev_b64 v[142:143], 10, v[140:141]
	v_lshl_add_u64 v[142:143], v[142:143], 0, v[138:139]
	v_cvt_f32_ubyte1_e32 v163, v192
	v_cvt_f32_ubyte0_e32 v162, v192
	v_pk_mul_f32 v[162:163], v[162:163], s[34:35] op_sel_hi:[1,0]
	s_nop 0
	v_pk_mul_f32 v[124:125], v[124:125], v[162:163]
	v_cvt_f32_ubyte3_e32 v163, v192
	v_cvt_f32_ubyte2_e32 v162, v192
	v_pk_mul_f32 v[162:163], v[162:163], s[34:35] op_sel_hi:[1,0]
	s_nop 0
	v_pk_mul_f32 v[126:127], v[126:127], v[162:163]
	v_cvt_f32_ubyte1_e32 v163, v193
	v_cvt_f32_ubyte0_e32 v162, v193
	v_pk_mul_f32 v[162:163], v[162:163], s[34:35] op_sel_hi:[1,0]
	s_nop 0
	v_pk_mul_f32 v[120:121], v[120:121], v[162:163]
	v_cvt_f32_ubyte3_e32 v163, v193
	v_cvt_f32_ubyte2_e32 v162, v193
	v_pk_mul_f32 v[160:161], v[162:163], s[34:35] op_sel_hi:[1,0]
	s_nop 0
	v_pk_mul_f32 v[122:123], v[122:123], v[160:161]
	s_cbranch_scc1 .LBB0_1608
	v_lshl_add_u64 v[160:161], v[142:143], 1, s[16:17]
	v_lshlrev_b32_e32 v164, 16, v208
	v_and_b32_e32 v165, 0xffff0000, v208
	v_lshlrev_b32_e32 v160, 16, v209
	v_and_b32_e32 v161, 0xffff0000, v209
	v_pk_add_f32 v[126:127], v[126:127], v[160:161]
	v_lshlrev_b32_e32 v160, 16, v210
	v_and_b32_e32 v161, 0xffff0000, v210
	v_pk_add_f32 v[120:121], v[120:121], v[160:161]
	v_lshlrev_b32_e32 v160, 16, v211
	v_and_b32_e32 v161, 0xffff0000, v211
	v_pk_add_f32 v[124:125], v[124:125], v[164:165]
	v_pk_add_f32 v[122:123], v[122:123], v[160:161]
.LBB0_1608:
	s_cmp_lt_i32 s2, 2
	s_cselect_b32 s35, s17, s44
	s_cselect_b32 s34, s16, s41
	v_cvt_pk_bf16_f32 v124, v124, v125
	v_cvt_pk_bf16_f32 v125, v126, v127
	v_cvt_pk_bf16_f32 v126, v120, v121
	v_cvt_pk_bf16_f32 v127, v122, v123
	v_lshl_add_u64 v[120:121], v[142:143], 1, s[34:35]
	global_store_dwordx4 v[120:121], v[124:127], off
	s_nop 1
	s_mov_b32 s2, 0x3b808081
	s_andn2_b64 vcc, exec, s[46:47]
	v_cvt_f32_ubyte1_e32 v125, v194
	v_cvt_f32_ubyte0_e32 v124, v194
	v_pk_mul_f32 v[124:125], v[124:125], s[2:3] op_sel_hi:[1,0]
	s_nop 0
	v_pk_mul_f32 v[116:117], v[116:117], v[124:125]
	v_cvt_f32_ubyte3_e32 v125, v194
	v_cvt_f32_ubyte2_e32 v124, v194
	v_pk_mul_f32 v[124:125], v[124:125], s[2:3] op_sel_hi:[1,0]
	s_nop 0
	v_pk_mul_f32 v[118:119], v[118:119], v[124:125]
	v_cvt_f32_ubyte1_e32 v125, v195
	v_cvt_f32_ubyte0_e32 v124, v195
	v_pk_mul_f32 v[124:125], v[124:125], s[2:3] op_sel_hi:[1,0]
	s_nop 0
	v_pk_mul_f32 v[112:113], v[112:113], v[124:125]
	v_cvt_f32_ubyte3_e32 v125, v195
	v_cvt_f32_ubyte2_e32 v124, v195
	v_pk_mul_f32 v[122:123], v[124:125], s[2:3] op_sel_hi:[1,0]
	s_nop 0
	v_pk_mul_f32 v[114:115], v[114:115], v[122:123]
	v_cndmask_b32_e64 v122, 0, 1, s[46:47]
	v_cmp_ne_u32_e64 s[2:3], 1, v122
	s_cbranch_vccnz .LBB0_1610
	v_lshlrev_b64 v[122:123], 1, v[142:143]
	v_or_b32_e32 v122, 0x100, v122
	v_lshl_add_u64 v[122:123], s[16:17], 0, v[122:123]
	v_lshlrev_b32_e32 v126, 16, v212
	v_and_b32_e32 v127, 0xffff0000, v212
	v_lshlrev_b32_e32 v122, 16, v213
	v_and_b32_e32 v123, 0xffff0000, v213
	v_pk_add_f32 v[118:119], v[118:119], v[122:123]
	v_lshlrev_b32_e32 v122, 16, v214
	v_and_b32_e32 v123, 0xffff0000, v214
	v_pk_add_f32 v[112:113], v[112:113], v[122:123]
	v_lshlrev_b32_e32 v122, 16, v215
	v_and_b32_e32 v123, 0xffff0000, v215
	v_pk_add_f32 v[116:117], v[116:117], v[126:127]
	v_pk_add_f32 v[114:115], v[114:115], v[122:123]
.LBB0_1610:
	v_cvt_pk_bf16_f32 v116, v116, v117
	v_cvt_pk_bf16_f32 v117, v118, v119
	v_cvt_pk_bf16_f32 v118, v112, v113
	v_cvt_pk_bf16_f32 v119, v114, v115
	global_store_dwordx4 v[120:121], v[116:119], off offset:256
	s_nop 1
	v_or_b32_e32 v112, 16, v156
	v_add_u32_e32 v114, s48, v112
	v_ashrrev_i32_e32 v115, 31, v114
	v_mov_b64_e32 v[116:117], s[14:15]
	s_movk_i32 s46, 0xc00
	v_lshlrev_b64 v[112:113], 10, v[114:115]
	v_mad_i64_i32 v[114:115], s[46:47], v114, s46, v[116:117]
	v_lshl_add_u64 v[114:115], v[114:115], 0, s[52:53]
	v_lshl_add_u64 v[114:115], v[114:115], 0, v[138:139]
	s_mov_b32 s46, 0x3b808081
	v_lshl_add_u64 v[112:113], v[112:113], 0, v[138:139]
	s_and_b64 vcc, exec, s[2:3]
	v_cvt_f32_ubyte1_e32 v119, v196
	v_cvt_f32_ubyte0_e32 v118, v196
	v_pk_mul_f32 v[118:119], v[118:119], s[46:47] op_sel_hi:[1,0]
	s_nop 0
	v_pk_mul_f32 v[108:109], v[108:109], v[118:119]
	v_cvt_f32_ubyte3_e32 v119, v196
	v_cvt_f32_ubyte2_e32 v118, v196
	v_pk_mul_f32 v[118:119], v[118:119], s[46:47] op_sel_hi:[1,0]
	s_nop 0
	v_pk_mul_f32 v[110:111], v[110:111], v[118:119]
	v_cvt_f32_ubyte1_e32 v119, v197
	v_cvt_f32_ubyte0_e32 v118, v197
	v_pk_mul_f32 v[118:119], v[118:119], s[46:47] op_sel_hi:[1,0]
	s_nop 0
	v_pk_mul_f32 v[104:105], v[104:105], v[118:119]
	v_cvt_f32_ubyte3_e32 v119, v197
	v_cvt_f32_ubyte2_e32 v118, v197
	v_pk_mul_f32 v[116:117], v[118:119], s[46:47] op_sel_hi:[1,0]
	s_nop 0
	v_pk_mul_f32 v[106:107], v[106:107], v[116:117]
	s_cbranch_vccnz .LBB0_1612
	v_lshl_add_u64 v[116:117], v[112:113], 1, s[16:17]
	v_lshlrev_b32_e32 v120, 16, v216
	v_and_b32_e32 v121, 0xffff0000, v216
	v_lshlrev_b32_e32 v116, 16, v217
	v_and_b32_e32 v117, 0xffff0000, v217
	v_pk_add_f32 v[110:111], v[110:111], v[116:117]
	v_lshlrev_b32_e32 v116, 16, v218
	v_and_b32_e32 v117, 0xffff0000, v218
	v_pk_add_f32 v[104:105], v[104:105], v[116:117]
	v_lshlrev_b32_e32 v116, 16, v219
	v_and_b32_e32 v117, 0xffff0000, v219
	v_pk_add_f32 v[108:109], v[108:109], v[120:121]
	v_pk_add_f32 v[106:107], v[106:107], v[116:117]
.LBB0_1612:
	v_cvt_pk_bf16_f32 v108, v108, v109
	v_cvt_pk_bf16_f32 v109, v110, v111
	v_cvt_pk_bf16_f32 v110, v104, v105
	v_cvt_pk_bf16_f32 v111, v106, v107
	v_lshl_add_u64 v[104:105], v[112:113], 1, s[34:35]
	global_store_dwordx4 v[104:105], v[108:111], off
	s_nop 1
	s_and_b64 vcc, exec, s[2:3]
	v_cvt_f32_ubyte1_e32 v109, v198
	v_cvt_f32_ubyte0_e32 v108, v198
	v_pk_mul_f32 v[108:109], v[108:109], s[46:47] op_sel_hi:[1,0]
	s_nop 0
	v_pk_mul_f32 v[100:101], v[100:101], v[108:109]
	v_cvt_f32_ubyte3_e32 v109, v198
	v_cvt_f32_ubyte2_e32 v108, v198
	v_pk_mul_f32 v[108:109], v[108:109], s[46:47] op_sel_hi:[1,0]
	s_nop 0
	v_pk_mul_f32 v[102:103], v[102:103], v[108:109]
	v_cvt_f32_ubyte1_e32 v109, v199
	v_cvt_f32_ubyte0_e32 v108, v199
	v_pk_mul_f32 v[108:109], v[108:109], s[46:47] op_sel_hi:[1,0]
	s_nop 0
	v_pk_mul_f32 v[96:97], v[96:97], v[108:109]
	v_cvt_f32_ubyte3_e32 v109, v199
	v_cvt_f32_ubyte2_e32 v108, v199
	v_pk_mul_f32 v[106:107], v[108:109], s[46:47] op_sel_hi:[1,0]
	s_nop 0
	v_pk_mul_f32 v[98:99], v[98:99], v[106:107]
	s_cbranch_vccnz .LBB0_1614
	v_lshlrev_b64 v[106:107], 1, v[112:113]
	v_or_b32_e32 v106, 0x100, v106
	v_lshl_add_u64 v[106:107], s[16:17], 0, v[106:107]
	v_lshlrev_b32_e32 v110, 16, v220
	v_and_b32_e32 v111, 0xffff0000, v220
	v_lshlrev_b32_e32 v106, 16, v221
	v_and_b32_e32 v107, 0xffff0000, v221
	v_pk_add_f32 v[102:103], v[102:103], v[106:107]
	v_lshlrev_b32_e32 v106, 16, v222
	v_and_b32_e32 v107, 0xffff0000, v222
	v_pk_add_f32 v[96:97], v[96:97], v[106:107]
	v_lshlrev_b32_e32 v106, 16, v223
	v_and_b32_e32 v107, 0xffff0000, v223
	v_pk_add_f32 v[100:101], v[100:101], v[110:111]
	v_pk_add_f32 v[98:99], v[98:99], v[106:107]
.LBB0_1614:
	v_cvt_pk_bf16_f32 v100, v100, v101
	v_cvt_pk_bf16_f32 v101, v102, v103
	v_cvt_pk_bf16_f32 v102, v96, v97
	v_cvt_pk_bf16_f32 v103, v98, v99
	global_store_dwordx4 v[104:105], v[100:103], off offset:256
	s_nop 1
	v_or_b32_e32 v96, 32, v156
	v_add_u32_e32 v98, s48, v96
	v_ashrrev_i32_e32 v99, 31, v98
	v_mov_b64_e32 v[100:101], s[14:15]
	s_movk_i32 s46, 0xc00
	v_lshlrev_b64 v[96:97], 10, v[98:99]
	v_mad_i64_i32 v[98:99], s[46:47], v98, s46, v[100:101]
	v_lshl_add_u64 v[98:99], v[98:99], 0, s[52:53]
	v_lshl_add_u64 v[98:99], v[98:99], 0, v[138:139]
	s_mov_b32 s46, 0x3b808081
	v_lshl_add_u64 v[96:97], v[96:97], 0, v[138:139]
	s_and_b64 vcc, exec, s[2:3]
	v_cvt_f32_ubyte1_e32 v103, v200
	v_cvt_f32_ubyte0_e32 v102, v200
	v_pk_mul_f32 v[102:103], v[102:103], s[46:47] op_sel_hi:[1,0]
	s_nop 0
	v_pk_mul_f32 v[92:93], v[92:93], v[102:103]
	v_cvt_f32_ubyte3_e32 v103, v200
	v_cvt_f32_ubyte2_e32 v102, v200
	v_pk_mul_f32 v[102:103], v[102:103], s[46:47] op_sel_hi:[1,0]
	s_nop 0
	v_pk_mul_f32 v[94:95], v[94:95], v[102:103]
	v_cvt_f32_ubyte1_e32 v103, v201
	v_cvt_f32_ubyte0_e32 v102, v201
	v_pk_mul_f32 v[102:103], v[102:103], s[46:47] op_sel_hi:[1,0]
	s_nop 0
	v_pk_mul_f32 v[88:89], v[88:89], v[102:103]
	v_cvt_f32_ubyte3_e32 v103, v201
	v_cvt_f32_ubyte2_e32 v102, v201
	v_pk_mul_f32 v[100:101], v[102:103], s[46:47] op_sel_hi:[1,0]
	s_nop 0
	v_pk_mul_f32 v[90:91], v[90:91], v[100:101]
	s_cbranch_vccnz .LBB0_1616
	v_lshl_add_u64 v[100:101], v[96:97], 1, s[16:17]
	v_lshlrev_b32_e32 v104, 16, v224
	v_and_b32_e32 v105, 0xffff0000, v224
	v_lshlrev_b32_e32 v100, 16, v225
	v_and_b32_e32 v101, 0xffff0000, v225
	v_pk_add_f32 v[94:95], v[94:95], v[100:101]
	v_lshlrev_b32_e32 v100, 16, v226
	v_and_b32_e32 v101, 0xffff0000, v226
	v_pk_add_f32 v[88:89], v[88:89], v[100:101]
	v_lshlrev_b32_e32 v100, 16, v227
	v_and_b32_e32 v101, 0xffff0000, v227
	v_pk_add_f32 v[92:93], v[92:93], v[104:105]
	v_pk_add_f32 v[90:91], v[90:91], v[100:101]
.LBB0_1616:
	v_cvt_pk_bf16_f32 v92, v92, v93
	v_cvt_pk_bf16_f32 v93, v94, v95
	v_cvt_pk_bf16_f32 v94, v88, v89
	v_cvt_pk_bf16_f32 v95, v90, v91
	v_lshl_add_u64 v[88:89], v[96:97], 1, s[34:35]
	global_store_dwordx4 v[88:89], v[92:95], off
	s_nop 1
	s_and_b64 vcc, exec, s[2:3]
	v_cvt_f32_ubyte1_e32 v93, v202
	v_cvt_f32_ubyte0_e32 v92, v202
	v_pk_mul_f32 v[92:93], v[92:93], s[46:47] op_sel_hi:[1,0]
	s_nop 0
	v_pk_mul_f32 v[84:85], v[84:85], v[92:93]
	v_cvt_f32_ubyte3_e32 v93, v202
	v_cvt_f32_ubyte2_e32 v92, v202
	v_pk_mul_f32 v[92:93], v[92:93], s[46:47] op_sel_hi:[1,0]
	s_nop 0
	v_pk_mul_f32 v[86:87], v[86:87], v[92:93]
	v_cvt_f32_ubyte1_e32 v93, v203
	v_cvt_f32_ubyte0_e32 v92, v203
	v_pk_mul_f32 v[92:93], v[92:93], s[46:47] op_sel_hi:[1,0]
	s_nop 0
	v_pk_mul_f32 v[80:81], v[80:81], v[92:93]
	v_cvt_f32_ubyte3_e32 v93, v203
	v_cvt_f32_ubyte2_e32 v92, v203
	v_pk_mul_f32 v[90:91], v[92:93], s[46:47] op_sel_hi:[1,0]
	s_nop 0
	v_pk_mul_f32 v[82:83], v[82:83], v[90:91]
	s_cbranch_vccnz .LBB0_1618
	v_lshlrev_b64 v[90:91], 1, v[96:97]
	v_or_b32_e32 v90, 0x100, v90
	v_lshl_add_u64 v[90:91], s[16:17], 0, v[90:91]
	v_lshlrev_b32_e32 v94, 16, v228
	v_and_b32_e32 v95, 0xffff0000, v228
	v_lshlrev_b32_e32 v90, 16, v229
	v_and_b32_e32 v91, 0xffff0000, v229
	v_pk_add_f32 v[86:87], v[86:87], v[90:91]
	v_lshlrev_b32_e32 v90, 16, v230
	v_and_b32_e32 v91, 0xffff0000, v230
	v_pk_add_f32 v[80:81], v[80:81], v[90:91]
	v_lshlrev_b32_e32 v90, 16, v231
	v_and_b32_e32 v91, 0xffff0000, v231
	v_pk_add_f32 v[84:85], v[84:85], v[94:95]
	v_pk_add_f32 v[82:83], v[82:83], v[90:91]
.LBB0_1618:
	v_cvt_pk_bf16_f32 v84, v84, v85
	v_cvt_pk_bf16_f32 v85, v86, v87
	v_cvt_pk_bf16_f32 v86, v80, v81
	v_cvt_pk_bf16_f32 v87, v82, v83
	global_store_dwordx4 v[88:89], v[84:87], off offset:256
	s_nop 1
	v_or_b32_e32 v80, 48, v156
	v_add_u32_e32 v82, s48, v80
	v_ashrrev_i32_e32 v83, 31, v82
	v_mov_b64_e32 v[84:85], s[14:15]
	s_movk_i32 s46, 0xc00
	v_lshlrev_b64 v[80:81], 10, v[82:83]
	v_mad_i64_i32 v[82:83], s[46:47], v82, s46, v[84:85]
	v_lshl_add_u64 v[82:83], v[82:83], 0, s[52:53]
	v_lshl_add_u64 v[82:83], v[82:83], 0, v[138:139]
	s_mov_b32 s46, 0x3b808081
	v_lshl_add_u64 v[80:81], v[80:81], 0, v[138:139]
	s_and_b64 vcc, exec, s[2:3]
	v_cvt_f32_ubyte1_e32 v87, v204
	v_cvt_f32_ubyte0_e32 v86, v204
	v_pk_mul_f32 v[86:87], v[86:87], s[46:47] op_sel_hi:[1,0]
	s_nop 0
	v_pk_mul_f32 v[76:77], v[76:77], v[86:87]
	v_cvt_f32_ubyte3_e32 v87, v204
	v_cvt_f32_ubyte2_e32 v86, v204
	v_pk_mul_f32 v[86:87], v[86:87], s[46:47] op_sel_hi:[1,0]
	s_nop 0
	v_pk_mul_f32 v[78:79], v[78:79], v[86:87]
	v_cvt_f32_ubyte1_e32 v87, v205
	v_cvt_f32_ubyte0_e32 v86, v205
	v_pk_mul_f32 v[86:87], v[86:87], s[46:47] op_sel_hi:[1,0]
	s_nop 0
	v_pk_mul_f32 v[72:73], v[72:73], v[86:87]
	v_cvt_f32_ubyte3_e32 v87, v205
	v_cvt_f32_ubyte2_e32 v86, v205
	v_pk_mul_f32 v[84:85], v[86:87], s[46:47] op_sel_hi:[1,0]
	s_nop 0
	v_pk_mul_f32 v[74:75], v[74:75], v[84:85]
	s_cbranch_vccnz .LBB0_1620
	v_lshl_add_u64 v[84:85], v[80:81], 1, s[16:17]
	v_lshlrev_b32_e32 v88, 16, v232
	v_and_b32_e32 v89, 0xffff0000, v232
	v_lshlrev_b32_e32 v84, 16, v233
	v_and_b32_e32 v85, 0xffff0000, v233
	v_pk_add_f32 v[78:79], v[78:79], v[84:85]
	v_lshlrev_b32_e32 v84, 16, v234
	v_and_b32_e32 v85, 0xffff0000, v234
	v_pk_add_f32 v[72:73], v[72:73], v[84:85]
	v_lshlrev_b32_e32 v84, 16, v235
	v_and_b32_e32 v85, 0xffff0000, v235
	v_pk_add_f32 v[76:77], v[76:77], v[88:89]
	v_pk_add_f32 v[74:75], v[74:75], v[84:85]
.LBB0_1620:
	v_cvt_pk_bf16_f32 v76, v76, v77
	v_cvt_pk_bf16_f32 v77, v78, v79
	v_cvt_pk_bf16_f32 v78, v72, v73
	v_cvt_pk_bf16_f32 v79, v74, v75
	v_lshl_add_u64 v[72:73], v[80:81], 1, s[34:35]
	global_store_dwordx4 v[72:73], v[76:79], off
	s_nop 1
	s_and_b64 vcc, exec, s[2:3]
	v_cvt_f32_ubyte1_e32 v77, v206
	v_cvt_f32_ubyte0_e32 v76, v206
	v_pk_mul_f32 v[76:77], v[76:77], s[46:47] op_sel_hi:[1,0]
	s_nop 0
	v_pk_mul_f32 v[68:69], v[68:69], v[76:77]
	v_cvt_f32_ubyte3_e32 v77, v206
	v_cvt_f32_ubyte2_e32 v76, v206
	v_pk_mul_f32 v[76:77], v[76:77], s[46:47] op_sel_hi:[1,0]
	s_nop 0
	v_pk_mul_f32 v[70:71], v[70:71], v[76:77]
	v_cvt_f32_ubyte1_e32 v77, v207
	v_cvt_f32_ubyte0_e32 v76, v207
	v_pk_mul_f32 v[76:77], v[76:77], s[46:47] op_sel_hi:[1,0]
	s_nop 0
	v_pk_mul_f32 v[64:65], v[64:65], v[76:77]
	v_cvt_f32_ubyte3_e32 v77, v207
	v_cvt_f32_ubyte2_e32 v76, v207
	v_pk_mul_f32 v[74:75], v[76:77], s[46:47] op_sel_hi:[1,0]
	s_nop 0
	v_pk_mul_f32 v[66:67], v[66:67], v[74:75]
	s_cbranch_vccnz .LBB0_1622
	v_lshlrev_b64 v[74:75], 1, v[80:81]
	v_or_b32_e32 v74, 0x100, v74
	v_lshl_add_u64 v[74:75], s[16:17], 0, v[74:75]
	v_lshlrev_b32_e32 v78, 16, v236
	v_and_b32_e32 v79, 0xffff0000, v236
	v_lshlrev_b32_e32 v74, 16, v237
	v_and_b32_e32 v75, 0xffff0000, v237
	v_pk_add_f32 v[70:71], v[70:71], v[74:75]
	v_lshlrev_b32_e32 v74, 16, v238
	v_and_b32_e32 v75, 0xffff0000, v238
	v_pk_add_f32 v[64:65], v[64:65], v[74:75]
	v_lshlrev_b32_e32 v74, 16, v239
	v_and_b32_e32 v75, 0xffff0000, v239
	v_pk_add_f32 v[68:69], v[68:69], v[78:79]
	v_pk_add_f32 v[66:67], v[66:67], v[74:75]
.LBB0_1622:
	v_cvt_pk_bf16_f32 v68, v68, v69
	v_cvt_pk_bf16_f32 v69, v70, v71
	v_cvt_pk_bf16_f32 v70, v64, v65
	v_cvt_pk_bf16_f32 v71, v66, v67
	global_store_dwordx4 v[72:73], v[68:71], off offset:256
	s_nop 1
	v_add_u32_e32 v240, 128, v140
	v_mov_b32_e32 v241, 0
	v_lshlrev_b64 v[240:241], 10, v[240:241]
	v_lshl_add_u64 v[242:243], v[240:241], 1, v[240:241]
	v_lshl_add_u64 v[242:243], v[242:243], 0, s[14:15]
	v_lshl_add_u64 v[242:243], v[242:243], 0, s[52:53]
	v_lshl_add_u64 v[242:243], v[242:243], 0, v[138:139]
	global_load_dwordx2 v[192:193], v[242:243], off
	global_load_dwordx2 v[194:195], v[242:243], off offset:128
	v_add_u32_e32 v240, 144, v140
	v_mov_b32_e32 v241, 0
	v_lshlrev_b64 v[240:241], 10, v[240:241]
	v_lshl_add_u64 v[242:243], v[240:241], 1, v[240:241]
	v_lshl_add_u64 v[242:243], v[242:243], 0, s[14:15]
	v_lshl_add_u64 v[242:243], v[242:243], 0, s[52:53]
	v_lshl_add_u64 v[242:243], v[242:243], 0, v[138:139]
	global_load_dwordx2 v[196:197], v[242:243], off
	global_load_dwordx2 v[198:199], v[242:243], off offset:128
	v_add_u32_e32 v240, 160, v140
	v_mov_b32_e32 v241, 0
	v_lshlrev_b64 v[240:241], 10, v[240:241]
	v_lshl_add_u64 v[242:243], v[240:241], 1, v[240:241]
	v_lshl_add_u64 v[242:243], v[242:243], 0, s[14:15]
	v_lshl_add_u64 v[242:243], v[242:243], 0, s[52:53]
	v_lshl_add_u64 v[242:243], v[242:243], 0, v[138:139]
	global_load_dwordx2 v[200:201], v[242:243], off
	global_load_dwordx2 v[202:203], v[242:243], off offset:128
	v_add_u32_e32 v240, 176, v140
	v_mov_b32_e32 v241, 0
	v_lshlrev_b64 v[240:241], 10, v[240:241]
	v_lshl_add_u64 v[242:243], v[240:241], 1, v[240:241]
	v_lshl_add_u64 v[242:243], v[242:243], 0, s[14:15]
	v_lshl_add_u64 v[242:243], v[242:243], 0, s[52:53]
	v_lshl_add_u64 v[242:243], v[242:243], 0, v[138:139]
	global_load_dwordx2 v[204:205], v[242:243], off
	global_load_dwordx2 v[206:207], v[242:243], off offset:128
	s_and_b64 vcc, exec, s[2:3]
	s_cbranch_vccnz .Lmy_pj_skipB
	v_add_u32_e32 v240, 128, v140
	v_mov_b32_e32 v241, 0
	v_lshlrev_b64 v[240:241], 10, v[240:241]
	v_lshl_add_u64 v[166:167], v[240:241], 0, v[138:139]
	v_lshl_add_u64 v[166:167], v[166:167], 1, s[16:17]
	global_load_dwordx4 v[208:211], v[166:167], off
	global_load_dwordx4 v[212:215], v[166:167], off offset:256
	v_add_u32_e32 v240, 144, v140
	v_mov_b32_e32 v241, 0
	v_lshlrev_b64 v[240:241], 10, v[240:241]
	v_lshl_add_u64 v[166:167], v[240:241], 0, v[138:139]
	v_lshl_add_u64 v[166:167], v[166:167], 1, s[16:17]
	global_load_dwordx4 v[216:219], v[166:167], off
	global_load_dwordx4 v[220:223], v[166:167], off offset:256
	v_add_u32_e32 v240, 160, v140
	v_mov_b32_e32 v241, 0
	v_lshlrev_b64 v[240:241], 10, v[240:241]
	v_lshl_add_u64 v[166:167], v[240:241], 0, v[138:139]
	v_lshl_add_u64 v[166:167], v[166:167], 1, s[16:17]
	global_load_dwordx4 v[224:227], v[166:167], off
	global_load_dwordx4 v[228:231], v[166:167], off offset:256
	v_add_u32_e32 v240, 176, v140
	v_mov_b32_e32 v241, 0
	v_lshlrev_b64 v[240:241], 10, v[240:241]
	v_lshl_add_u64 v[166:167], v[240:241], 0, v[138:139]
	v_lshl_add_u64 v[166:167], v[166:167], 1, s[16:17]
	global_load_dwordx4 v[232:235], v[166:167], off
	global_load_dwordx4 v[236:239], v[166:167], off offset:256
.Lmy_pj_skipB:
	s_waitcnt vmcnt(0)
	v_add_u32_e32 v66, 0x80, v140
	v_ashrrev_i32_e32 v67, 31, v66
	v_mov_b64_e32 v[68:69], s[14:15]
	s_movk_i32 s46, 0xc00
	v_lshlrev_b64 v[64:65], 10, v[66:67]
	v_mad_i64_i32 v[66:67], s[46:47], v66, s46, v[68:69]
	v_lshl_add_u64 v[66:67], v[66:67], 0, s[52:53]
	v_lshl_add_u64 v[66:67], v[66:67], 0, v[138:139]
	s_mov_b32 s46, 0x3b808081
	v_lshl_add_u64 v[64:65], v[64:65], 0, v[138:139]
	s_and_b64 vcc, exec, s[2:3]
	v_cvt_f32_ubyte1_e32 v71, v192
	v_cvt_f32_ubyte0_e32 v70, v192
	v_pk_mul_f32 v[70:71], v[70:71], s[46:47] op_sel_hi:[1,0]
	s_nop 0
	v_pk_mul_f32 v[60:61], v[60:61], v[70:71]
	v_cvt_f32_ubyte3_e32 v71, v192
	v_cvt_f32_ubyte2_e32 v70, v192
	v_pk_mul_f32 v[70:71], v[70:71], s[46:47] op_sel_hi:[1,0]
	s_nop 0
	v_pk_mul_f32 v[62:63], v[62:63], v[70:71]
	v_cvt_f32_ubyte1_e32 v71, v193
	v_cvt_f32_ubyte0_e32 v70, v193
	v_pk_mul_f32 v[70:71], v[70:71], s[46:47] op_sel_hi:[1,0]
	s_nop 0
	v_pk_mul_f32 v[56:57], v[56:57], v[70:71]
	v_cvt_f32_ubyte3_e32 v71, v193
	v_cvt_f32_ubyte2_e32 v70, v193
	v_pk_mul_f32 v[68:69], v[70:71], s[46:47] op_sel_hi:[1,0]
	s_nop 0
	v_pk_mul_f32 v[58:59], v[58:59], v[68:69]
	s_cbranch_vccnz .LBB0_1624
	v_lshl_add_u64 v[68:69], v[64:65], 1, s[16:17]
	v_lshlrev_b32_e32 v72, 16, v208
	v_and_b32_e32 v73, 0xffff0000, v208
	v_lshlrev_b32_e32 v68, 16, v209
	v_and_b32_e32 v69, 0xffff0000, v209
	v_pk_add_f32 v[62:63], v[62:63], v[68:69]
	v_lshlrev_b32_e32 v68, 16, v210
	v_and_b32_e32 v69, 0xffff0000, v210
	v_pk_add_f32 v[56:57], v[56:57], v[68:69]
	v_lshlrev_b32_e32 v68, 16, v211
	v_and_b32_e32 v69, 0xffff0000, v211
	v_pk_add_f32 v[60:61], v[60:61], v[72:73]
	v_pk_add_f32 v[58:59], v[58:59], v[68:69]
.LBB0_1624:
	v_cvt_pk_bf16_f32 v60, v60, v61
	v_cvt_pk_bf16_f32 v61, v62, v63
	v_cvt_pk_bf16_f32 v62, v56, v57
	v_cvt_pk_bf16_f32 v63, v58, v59
	v_lshl_add_u64 v[56:57], v[64:65], 1, s[34:35]
	global_store_dwordx4 v[56:57], v[60:63], off
	s_nop 1
	s_and_b64 vcc, exec, s[2:3]
	v_cvt_f32_ubyte1_e32 v61, v194
	v_cvt_f32_ubyte0_e32 v60, v194
	v_pk_mul_f32 v[60:61], v[60:61], s[46:47] op_sel_hi:[1,0]
	s_nop 0
	v_pk_mul_f32 v[52:53], v[52:53], v[60:61]
	v_cvt_f32_ubyte3_e32 v61, v194
	v_cvt_f32_ubyte2_e32 v60, v194
	v_pk_mul_f32 v[60:61], v[60:61], s[46:47] op_sel_hi:[1,0]
	s_nop 0
	v_pk_mul_f32 v[54:55], v[54:55], v[60:61]
	v_cvt_f32_ubyte1_e32 v61, v195
	v_cvt_f32_ubyte0_e32 v60, v195
	v_pk_mul_f32 v[60:61], v[60:61], s[46:47] op_sel_hi:[1,0]
	s_nop 0
	v_pk_mul_f32 v[48:49], v[48:49], v[60:61]
	v_cvt_f32_ubyte3_e32 v61, v195
	v_cvt_f32_ubyte2_e32 v60, v195
	v_pk_mul_f32 v[58:59], v[60:61], s[46:47] op_sel_hi:[1,0]
	s_nop 0
	v_pk_mul_f32 v[50:51], v[50:51], v[58:59]
	s_cbranch_vccnz .LBB0_1626
	v_lshlrev_b64 v[58:59], 1, v[64:65]
	v_or_b32_e32 v58, 0x100, v58
	v_lshl_add_u64 v[58:59], s[16:17], 0, v[58:59]
	v_lshlrev_b32_e32 v62, 16, v212
	v_and_b32_e32 v63, 0xffff0000, v212
	v_lshlrev_b32_e32 v58, 16, v213
	v_and_b32_e32 v59, 0xffff0000, v213
	v_pk_add_f32 v[54:55], v[54:55], v[58:59]
	v_lshlrev_b32_e32 v58, 16, v214
	v_and_b32_e32 v59, 0xffff0000, v214
	v_pk_add_f32 v[48:49], v[48:49], v[58:59]
	v_lshlrev_b32_e32 v58, 16, v215
	v_and_b32_e32 v59, 0xffff0000, v215
	v_pk_add_f32 v[52:53], v[52:53], v[62:63]
	v_pk_add_f32 v[50:51], v[50:51], v[58:59]
.LBB0_1626:
	v_cvt_pk_bf16_f32 v52, v52, v53
	v_cvt_pk_bf16_f32 v53, v54, v55
	v_cvt_pk_bf16_f32 v54, v48, v49
	v_cvt_pk_bf16_f32 v55, v50, v51
	global_store_dwordx4 v[56:57], v[52:55], off offset:256
	s_nop 1
	v_add_u32_e32 v50, 0x90, v140
	v_ashrrev_i32_e32 v51, 31, v50
	v_mov_b64_e32 v[52:53], s[14:15]
	s_movk_i32 s46, 0xc00
	v_lshlrev_b64 v[48:49], 10, v[50:51]
	v_mad_i64_i32 v[50:51], s[46:47], v50, s46, v[52:53]
	v_lshl_add_u64 v[50:51], v[50:51], 0, s[52:53]
	v_lshl_add_u64 v[50:51], v[50:51], 0, v[138:139]
	s_mov_b32 s46, 0x3b808081
	v_lshl_add_u64 v[48:49], v[48:49], 0, v[138:139]
	s_and_b64 vcc, exec, s[2:3]
	v_cvt_f32_ubyte1_e32 v55, v196
	v_cvt_f32_ubyte0_e32 v54, v196
	v_pk_mul_f32 v[54:55], v[54:55], s[46:47] op_sel_hi:[1,0]
	s_nop 0
	v_pk_mul_f32 v[44:45], v[44:45], v[54:55]
	v_cvt_f32_ubyte3_e32 v55, v196
	v_cvt_f32_ubyte2_e32 v54, v196
	v_pk_mul_f32 v[54:55], v[54:55], s[46:47] op_sel_hi:[1,0]
	s_nop 0
	v_pk_mul_f32 v[46:47], v[46:47], v[54:55]
	v_cvt_f32_ubyte1_e32 v55, v197
	v_cvt_f32_ubyte0_e32 v54, v197
	v_pk_mul_f32 v[54:55], v[54:55], s[46:47] op_sel_hi:[1,0]
	s_nop 0
	v_pk_mul_f32 v[40:41], v[40:41], v[54:55]
	v_cvt_f32_ubyte3_e32 v55, v197
	v_cvt_f32_ubyte2_e32 v54, v197
	v_pk_mul_f32 v[52:53], v[54:55], s[46:47] op_sel_hi:[1,0]
	s_nop 0
	v_pk_mul_f32 v[42:43], v[42:43], v[52:53]
	s_cbranch_vccnz .LBB0_1628
	v_lshl_add_u64 v[52:53], v[48:49], 1, s[16:17]
	v_lshlrev_b32_e32 v56, 16, v216
	v_and_b32_e32 v57, 0xffff0000, v216
	v_lshlrev_b32_e32 v52, 16, v217
	v_and_b32_e32 v53, 0xffff0000, v217
	v_pk_add_f32 v[46:47], v[46:47], v[52:53]
	v_lshlrev_b32_e32 v52, 16, v218
	v_and_b32_e32 v53, 0xffff0000, v218
	v_pk_add_f32 v[40:41], v[40:41], v[52:53]
	v_lshlrev_b32_e32 v52, 16, v219
	v_and_b32_e32 v53, 0xffff0000, v219
	v_pk_add_f32 v[44:45], v[44:45], v[56:57]
	v_pk_add_f32 v[42:43], v[42:43], v[52:53]
.LBB0_1628:
	v_cvt_pk_bf16_f32 v44, v44, v45
	v_cvt_pk_bf16_f32 v45, v46, v47
	v_cvt_pk_bf16_f32 v46, v40, v41
	v_cvt_pk_bf16_f32 v47, v42, v43
	v_lshl_add_u64 v[40:41], v[48:49], 1, s[34:35]
	global_store_dwordx4 v[40:41], v[44:47], off
	s_nop 1
	s_and_b64 vcc, exec, s[2:3]
	v_cvt_f32_ubyte1_e32 v45, v198
	v_cvt_f32_ubyte0_e32 v44, v198
	v_pk_mul_f32 v[44:45], v[44:45], s[46:47] op_sel_hi:[1,0]
	s_nop 0
	v_pk_mul_f32 v[36:37], v[36:37], v[44:45]
	v_cvt_f32_ubyte3_e32 v45, v198
	v_cvt_f32_ubyte2_e32 v44, v198
	v_pk_mul_f32 v[44:45], v[44:45], s[46:47] op_sel_hi:[1,0]
	s_nop 0
	v_pk_mul_f32 v[38:39], v[38:39], v[44:45]
	v_cvt_f32_ubyte1_e32 v45, v199
	v_cvt_f32_ubyte0_e32 v44, v199
	v_pk_mul_f32 v[44:45], v[44:45], s[46:47] op_sel_hi:[1,0]
	s_nop 0
	v_pk_mul_f32 v[32:33], v[32:33], v[44:45]
	v_cvt_f32_ubyte3_e32 v45, v199
	v_cvt_f32_ubyte2_e32 v44, v199
	v_pk_mul_f32 v[42:43], v[44:45], s[46:47] op_sel_hi:[1,0]
	s_nop 0
	v_pk_mul_f32 v[34:35], v[34:35], v[42:43]
	s_cbranch_vccnz .LBB0_1630
	v_lshlrev_b64 v[42:43], 1, v[48:49]
	v_or_b32_e32 v42, 0x100, v42
	v_lshl_add_u64 v[42:43], s[16:17], 0, v[42:43]
	v_lshlrev_b32_e32 v46, 16, v220
	v_and_b32_e32 v47, 0xffff0000, v220
	v_lshlrev_b32_e32 v42, 16, v221
	v_and_b32_e32 v43, 0xffff0000, v221
	v_pk_add_f32 v[38:39], v[38:39], v[42:43]
	v_lshlrev_b32_e32 v42, 16, v222
	v_and_b32_e32 v43, 0xffff0000, v222
	v_pk_add_f32 v[32:33], v[32:33], v[42:43]
	v_lshlrev_b32_e32 v42, 16, v223
	v_and_b32_e32 v43, 0xffff0000, v223
	v_pk_add_f32 v[36:37], v[36:37], v[46:47]
	v_pk_add_f32 v[34:35], v[34:35], v[42:43]
.LBB0_1630:
	v_cvt_pk_bf16_f32 v36, v36, v37
	v_cvt_pk_bf16_f32 v37, v38, v39
	v_cvt_pk_bf16_f32 v38, v32, v33
	v_cvt_pk_bf16_f32 v39, v34, v35
	global_store_dwordx4 v[40:41], v[36:39], off offset:256
	s_nop 1
	v_add_u32_e32 v34, 0xa0, v140
	v_ashrrev_i32_e32 v35, 31, v34
	v_mov_b64_e32 v[36:37], s[14:15]
	s_movk_i32 s46, 0xc00
	v_lshlrev_b64 v[32:33], 10, v[34:35]
	v_mad_i64_i32 v[34:35], s[46:47], v34, s46, v[36:37]
	v_lshl_add_u64 v[34:35], v[34:35], 0, s[52:53]
	v_lshl_add_u64 v[34:35], v[34:35], 0, v[138:139]
	s_mov_b32 s46, 0x3b808081
	v_lshl_add_u64 v[32:33], v[32:33], 0, v[138:139]
	s_and_b64 vcc, exec, s[2:3]
	v_cvt_f32_ubyte1_e32 v39, v200
	v_cvt_f32_ubyte0_e32 v38, v200
	v_pk_mul_f32 v[38:39], v[38:39], s[46:47] op_sel_hi:[1,0]
	s_nop 0
	v_pk_mul_f32 v[28:29], v[28:29], v[38:39]
	v_cvt_f32_ubyte3_e32 v39, v200
	v_cvt_f32_ubyte2_e32 v38, v200
	v_pk_mul_f32 v[38:39], v[38:39], s[46:47] op_sel_hi:[1,0]
	s_nop 0
	v_pk_mul_f32 v[30:31], v[30:31], v[38:39]
	v_cvt_f32_ubyte1_e32 v39, v201
	v_cvt_f32_ubyte0_e32 v38, v201
	v_pk_mul_f32 v[38:39], v[38:39], s[46:47] op_sel_hi:[1,0]
	s_nop 0
	v_pk_mul_f32 v[24:25], v[24:25], v[38:39]
	v_cvt_f32_ubyte3_e32 v39, v201
	v_cvt_f32_ubyte2_e32 v38, v201
	v_pk_mul_f32 v[36:37], v[38:39], s[46:47] op_sel_hi:[1,0]
	s_nop 0
	v_pk_mul_f32 v[26:27], v[26:27], v[36:37]
	s_cbranch_vccnz .LBB0_1632
	v_lshl_add_u64 v[36:37], v[32:33], 1, s[16:17]
	v_lshlrev_b32_e32 v40, 16, v224
	v_and_b32_e32 v41, 0xffff0000, v224
	v_lshlrev_b32_e32 v36, 16, v225
	v_and_b32_e32 v37, 0xffff0000, v225
	v_pk_add_f32 v[30:31], v[30:31], v[36:37]
	v_lshlrev_b32_e32 v36, 16, v226
	v_and_b32_e32 v37, 0xffff0000, v226
	v_pk_add_f32 v[24:25], v[24:25], v[36:37]
	v_lshlrev_b32_e32 v36, 16, v227
	v_and_b32_e32 v37, 0xffff0000, v227
	v_pk_add_f32 v[28:29], v[28:29], v[40:41]
	v_pk_add_f32 v[26:27], v[26:27], v[36:37]
.LBB0_1632:
	v_cvt_pk_bf16_f32 v28, v28, v29
	v_cvt_pk_bf16_f32 v29, v30, v31
	v_cvt_pk_bf16_f32 v30, v24, v25
	v_cvt_pk_bf16_f32 v31, v26, v27
	v_lshl_add_u64 v[24:25], v[32:33], 1, s[34:35]
	global_store_dwordx4 v[24:25], v[28:31], off
	s_nop 1
	s_and_b64 vcc, exec, s[2:3]
	v_cvt_f32_ubyte1_e32 v29, v202
	v_cvt_f32_ubyte0_e32 v28, v202
	v_pk_mul_f32 v[28:29], v[28:29], s[46:47] op_sel_hi:[1,0]
	s_nop 0
	v_pk_mul_f32 v[20:21], v[20:21], v[28:29]
	v_cvt_f32_ubyte3_e32 v29, v202
	v_cvt_f32_ubyte2_e32 v28, v202
	v_pk_mul_f32 v[28:29], v[28:29], s[46:47] op_sel_hi:[1,0]
	s_nop 0
	v_pk_mul_f32 v[22:23], v[22:23], v[28:29]
	v_cvt_f32_ubyte1_e32 v29, v203
	v_cvt_f32_ubyte0_e32 v28, v203
	v_pk_mul_f32 v[28:29], v[28:29], s[46:47] op_sel_hi:[1,0]
	s_nop 0
	v_pk_mul_f32 v[16:17], v[16:17], v[28:29]
	v_cvt_f32_ubyte3_e32 v29, v203
	v_cvt_f32_ubyte2_e32 v28, v203
	v_pk_mul_f32 v[26:27], v[28:29], s[46:47] op_sel_hi:[1,0]
	s_nop 0
	v_pk_mul_f32 v[18:19], v[18:19], v[26:27]
	s_cbranch_vccnz .LBB0_1634
	v_lshlrev_b64 v[26:27], 1, v[32:33]
	v_or_b32_e32 v26, 0x100, v26
	v_lshl_add_u64 v[26:27], s[16:17], 0, v[26:27]
	v_lshlrev_b32_e32 v30, 16, v228
	v_and_b32_e32 v31, 0xffff0000, v228
	v_lshlrev_b32_e32 v26, 16, v229
	v_and_b32_e32 v27, 0xffff0000, v229
	v_pk_add_f32 v[22:23], v[22:23], v[26:27]
	v_lshlrev_b32_e32 v26, 16, v230
	v_and_b32_e32 v27, 0xffff0000, v230
	v_pk_add_f32 v[16:17], v[16:17], v[26:27]
	v_lshlrev_b32_e32 v26, 16, v231
	v_and_b32_e32 v27, 0xffff0000, v231
	v_pk_add_f32 v[20:21], v[20:21], v[30:31]
	v_pk_add_f32 v[18:19], v[18:19], v[26:27]
; #define PG8_WAIT_V(n) asm volatile("s_waitcnt vmcnt(" #n ")" ::: "memory")
; template <class Epi, class Sched>
; __device__ __forceinline__ void gemm_phase(int wid_s, PG8_LAS unsigned char* lds, const Gemm g, const Sched& S, const Epi& E) {
;     ...
;     for (;;) {
;         const bool has_next = S.next(ui + 1, nxt);
;         const char* nA = has_next ? (const char*)g.A + (size_t)nxt.pm * tstepA + nxt.ao : cA; const char* nB = has_next ? (const char*)g.Bt + (size_t)nxt.pn * tstepB + nxt.bo : cB;
; #pragma unroll 1
;         for (int t = 0; t < nt; t += 2) {
;             const bool last = (t == nt - 2);
;             const char* a1 = cA + (size_t)(t + 1) * kstep;
;             const char* a2 = last ? nA : cA + (size_t)(t + 2) * kstep; const char* b2 = last ? nB : cB + (size_t)(t + 2) * kstep;
;             const char* a3 = a2 + kstep; const char* b3 = b2 + kstep;
;             PG8_LDB(B0, 0, 0); PG8_LDB(B1, 0, 1); PG8_SCHED; PG8_LDA(At, 0, 0); PG8_STAGE(PG8_SA(1, 1), a1 + hstepA, voffA);
;             PG8_WAIT_V(8); PG8_WAIT_L(0); PG8_BAR; PG8_MMA(0, 0, At, B0); PG8_MMA(0, 1, At, B1); PG8_BAR; PG8_SCHED;
;             PG8_LDA(At, 0, 1); PG8_STAGE(PG8_SB(0, 0), b2, voffB); PG8_STAGE(PG8_SB(0, 1), b2 + hstepB, voffB); PG8_STAGE(PG8_SA(0, 0), a2, voffA);
;             PG8_WAIT_V(8); PG8_WAIT_L(0); PG8_BAR; PG8_MMA(1, 0, At, B0); PG8_MMA(1, 1, At, B1); PG8_BAR; PG8_SCHED;
;             PG8_LDB(B0, 1, 0); PG8_LDB(B1, 1, 1); PG8_SCHED; PG8_LDA(At, 1, 0); PG8_STAGE(PG8_SA(0, 1), a2 + hstepA, voffA);
;             PG8_WAIT_V(8); PG8_WAIT_L(0); PG8_BAR; PG8_MMA(0, 0, At, B0); PG8_MMA(0, 1, At, B1); PG8_BAR; PG8_SCHED;
;             PG8_LDA(At, 1, 1); PG8_STAGE(PG8_SB(1, 0), b3, voffB); PG8_STAGE(PG8_SB(1, 1), b3 + hstepB, voffB); PG8_STAGE(PG8_SA(1, 0), a3, voffA);
;             PG8_WAIT_V(8); PG8_WAIT_L(0); PG8_BAR; PG8_MMA(1, 0, At, B0); PG8_MMA(1, 1, At, B1); PG8_BAR; PG8_SCHED;
;         }
;         if (wr == 0) PG8_BAR;
;         E(acc, cur, wr, wc, fr, fq);
;         if (!has_next) break;
; #pragma unroll
;         for (int a = 0; a < 2; ++a)
; #pragma unroll
;             for (int b = 0; b < 2; ++b)
; #pragma unroll
;                 for (int m = 0; m < 4; ++m)
; #pragma unroll
;                     for (int n = 0; n < 2; ++n) acc[a][b][m][n] = (f32x4){0.f, 0.f, 0.f, 0.f};
;         cur = nxt; cA = nA; cB = nB; ++ui;
;         if (wr == 1) PG8_BAR;
;     }
.LBB0_1634:
	v_cvt_pk_bf16_f32 v20, v20, v21
	v_cvt_pk_bf16_f32 v21, v22, v23
	v_cvt_pk_bf16_f32 v22, v16, v17
	v_cvt_pk_bf16_f32 v23, v18, v19
	global_store_dwordx4 v[24:25], v[20:23], off offset:256
	s_nop 1
	v_add_u32_e32 v18, 0xb0, v140
	v_ashrrev_i32_e32 v19, 31, v18
	v_mov_b64_e32 v[20:21], s[14:15]
	s_movk_i32 s46, 0xc00
	v_lshlrev_b64 v[16:17], 10, v[18:19]
	v_mad_i64_i32 v[18:19], s[46:47], v18, s46, v[20:21]
	v_lshl_add_u64 v[18:19], v[18:19], 0, s[52:53]
	v_lshl_add_u64 v[18:19], v[18:19], 0, v[138:139]
	s_mov_b32 s46, 0x3b808081
	v_lshl_add_u64 v[16:17], v[16:17], 0, v[138:139]
	s_and_b64 vcc, exec, s[2:3]
	v_cvt_f32_ubyte1_e32 v23, v204
	v_cvt_f32_ubyte0_e32 v22, v204
	v_pk_mul_f32 v[22:23], v[22:23], s[46:47] op_sel_hi:[1,0]
	s_nop 0
	v_pk_mul_f32 v[12:13], v[12:13], v[22:23]
	v_cvt_f32_ubyte3_e32 v23, v204
	v_cvt_f32_ubyte2_e32 v22, v204
	v_pk_mul_f32 v[22:23], v[22:23], s[46:47] op_sel_hi:[1,0]
	s_nop 0
	v_pk_mul_f32 v[14:15], v[14:15], v[22:23]
	v_cvt_f32_ubyte1_e32 v23, v205
	v_cvt_f32_ubyte0_e32 v22, v205
	v_pk_mul_f32 v[22:23], v[22:23], s[46:47] op_sel_hi:[1,0]
	s_nop 0
	v_pk_mul_f32 v[8:9], v[8:9], v[22:23]
	v_cvt_f32_ubyte3_e32 v23, v205
	v_cvt_f32_ubyte2_e32 v22, v205
	v_pk_mul_f32 v[20:21], v[22:23], s[46:47] op_sel_hi:[1,0]
	s_nop 0
	v_pk_mul_f32 v[10:11], v[10:11], v[20:21]
	s_cbranch_vccnz .LBB0_1636
	v_lshl_add_u64 v[20:21], v[16:17], 1, s[16:17]
	v_lshlrev_b32_e32 v24, 16, v232
	v_and_b32_e32 v25, 0xffff0000, v232
	v_lshlrev_b32_e32 v20, 16, v233
	v_and_b32_e32 v21, 0xffff0000, v233
	v_pk_add_f32 v[14:15], v[14:15], v[20:21]
	v_lshlrev_b32_e32 v20, 16, v234
	v_and_b32_e32 v21, 0xffff0000, v234
	v_pk_add_f32 v[8:9], v[8:9], v[20:21]
	v_lshlrev_b32_e32 v20, 16, v235
	v_and_b32_e32 v21, 0xffff0000, v235
	v_pk_add_f32 v[12:13], v[12:13], v[24:25]
	v_pk_add_f32 v[10:11], v[10:11], v[20:21]
.LBB0_1636:
	v_cvt_pk_bf16_f32 v12, v12, v13
	v_cvt_pk_bf16_f32 v13, v14, v15
	v_cvt_pk_bf16_f32 v14, v8, v9
	v_cvt_pk_bf16_f32 v15, v10, v11
	v_lshl_add_u64 v[8:9], v[16:17], 1, s[34:35]
	global_store_dwordx4 v[8:9], v[12:15], off
	s_nop 1
	s_mov_b32 s34, 0x3b808081
	s_and_b64 vcc, exec, s[2:3]
	v_cvt_f32_ubyte1_e32 v13, v206
	v_cvt_f32_ubyte0_e32 v12, v206
	v_pk_mul_f32 v[12:13], v[12:13], s[34:35] op_sel_hi:[1,0]
	s_nop 0
	v_pk_mul_f32 v[4:5], v[4:5], v[12:13]
	v_cvt_f32_ubyte3_e32 v13, v206
	v_cvt_f32_ubyte2_e32 v12, v206
	v_pk_mul_f32 v[12:13], v[12:13], s[34:35] op_sel_hi:[1,0]
	s_nop 0
	v_pk_mul_f32 v[6:7], v[6:7], v[12:13]
	v_cvt_f32_ubyte1_e32 v13, v207
	v_cvt_f32_ubyte0_e32 v12, v207
	v_pk_mul_f32 v[12:13], v[12:13], s[34:35] op_sel_hi:[1,0]
	s_nop 0
	v_pk_mul_f32 v[0:1], v[0:1], v[12:13]
	v_cvt_f32_ubyte3_e32 v13, v207
	v_cvt_f32_ubyte2_e32 v12, v207
	v_pk_mul_f32 v[10:11], v[12:13], s[34:35] op_sel_hi:[1,0]
	s_nop 0
	v_pk_mul_f32 v[2:3], v[2:3], v[10:11]
	s_cbranch_vccnz .LBB0_1638
	v_lshlrev_b64 v[10:11], 1, v[16:17]
	v_or_b32_e32 v10, 0x100, v10
	v_lshl_add_u64 v[10:11], s[16:17], 0, v[10:11]
	v_lshlrev_b32_e32 v14, 16, v236
	v_and_b32_e32 v15, 0xffff0000, v236
	v_lshlrev_b32_e32 v10, 16, v237
	v_and_b32_e32 v11, 0xffff0000, v237
	v_pk_add_f32 v[6:7], v[6:7], v[10:11]
	v_lshlrev_b32_e32 v10, 16, v238
	v_and_b32_e32 v11, 0xffff0000, v238
	v_pk_add_f32 v[0:1], v[0:1], v[10:11]
	v_lshlrev_b32_e32 v10, 16, v239
	v_and_b32_e32 v11, 0xffff0000, v239
	v_pk_add_f32 v[4:5], v[4:5], v[14:15]
	v_pk_add_f32 v[2:3], v[2:3], v[10:11]
.LBB0_1638:
	v_cvt_pk_bf16_f32 v4, v4, v5
	v_cvt_pk_bf16_f32 v5, v6, v7
	v_cvt_pk_bf16_f32 v6, v0, v1
	v_cvt_pk_bf16_f32 v7, v2, v3
	s_cmp_eq_u32 s92, 2
	s_mov_b64 s[2:3], -1
	global_store_dwordx4 v[8:9], v[4:7], off offset:256
	s_nop 1
	s_cbranch_scc1 .LBB0_1593
	s_andn2_b64 vcc, exec, s[12:13]
	s_cbranch_vccnz .LBB0_1592
	s_barrier
	s_branch .LBB0_1592
